# GEMM K-loops: removed the back-to-back s_setprio 0 / s_setprio 1 pair between MFMA 16 and 17 of each 32-MFMA segment (priority state unchanged), on top of v009
# speedup vs baseline: 1.0103x; 1.0103x over previous
; #define PG8_STAGE(bufoff, gbase, voff) do { _Pragma("unroll") for (int _i = 0; _i < 2; ++_i) \
;         __builtin_amdgcn_global_load_lds((const unsigned*)((const char*)(gbase) + (voff)[_i]), (LAS unsigned*)(lds + (bufoff) + ldsw + _i * 8192), 16, 0, 0); } while (0)
; #define PG8_LDA(dst, b, h) do { _Pragma("unroll") for (int m = 0; m < 4; ++m) _Pragma("unroll") for (int k = 0; k < 2; ++k) dst[m][k] = *(const LAS bf16x8*)(lds + PG8_SA(b, h) + aoff + m * 2048 + k * 1024); } while (0)
; #define PG8_LDB(dst, b, h) do { _Pragma("unroll") for (int n = 0; n < 2; ++n) _Pragma("unroll") for (int k = 0; k < 2; ++k) dst[n][k] = *(const LAS bf16x8*)(lds + PG8_SB(b, h) + boff + n * 2048 + k * 1024); } while (0)
; #define PG8_WAIT_V(n) asm volatile("s_waitcnt vmcnt(" #n ")" ::: "memory")
; #define PG8_WAIT_L(n) asm volatile("s_waitcnt lgkmcnt(" #n ")" ::: "memory")
; #define PG8_BAR __builtin_amdgcn_s_barrier()
; #define PG8_SCHED __builtin_amdgcn_sched_barrier(0)
; template <class Epi, class Sched, bool I8 = false>
; __device__ __forceinline__ void gemm_phase(LAS unsigned char* lds, const Gemm g, const Sched& S, const Epi& E) {
;     ...
;         for (int t = 0; t < nt; t += 2) {
;             const bool last = (t == nt - 2);
;             const char* a1 = cA + (size_t)(t + 1) * kstep;
;             const char* a2 = last ? nA : cA + (size_t)(t + 2) * kstep; const char* b2 = last ? nB : cB + (size_t)(t + 2) * kstep;
;             const char* a3 = a2 + kstep; const char* b3 = b2 + kstep;
;             PG8_LDB(B0, 0, 0); PG8_LDB(B1, 0, 1); PG8_SCHED; PG8_LDA(At, 0, 0); PG8_STAGE(PG8_SA(1, 1), a1 + hstepA, voffA);
;             PG8_WAIT_V(8); PG8_WAIT_L(0); PG8_BAR; PG8_MMA(0, 0, At, B0); PG8_MMA(0, 1, At, B1); PG8_BAR; PG8_SCHED;
;             PG8_LDA(At, 0, 1); PG8_STAGE(PG8_SB(0, 0), b2, voffB); PG8_STAGE(PG8_SB(0, 1), b2 + hstepB, voffB); PG8_STAGE(PG8_SA(0, 0), a2, voffA);
;             PG8_WAIT_V(8); PG8_WAIT_L(0); PG8_BAR; PG8_MMA(1, 0, At, B0); PG8_MMA(1, 1, At, B1); PG8_BAR; PG8_SCHED;
.LBB0_1169:
	ds_read_b128 v[90:93], v169
	ds_read_b128 v[98:101], v169 offset:1024
	ds_read_b128 v[172:175], v169 offset:2048
	ds_read_b128 v[176:179], v169 offset:3072
	ds_read_b128 v[180:183], v170
	ds_read_b128 v[184:187], v170 offset:1024
	ds_read_b128 v[188:191], v170 offset:2048
	ds_read_b128 v[192:195], v170 offset:3072
	s_add_u32 s22, s20, 0x4000
	s_addc_u32 s23, s21, 0
	s_cmp_eq_u32 s53, 28
	s_cselect_b32 s26, s49, s22
	s_cselect_b32 s27, s13, s23
	s_cselect_b32 s24, s50, s51
	s_cselect_b32 s25, s11, s52
	s_add_u32 s22, s26, 0x8000
	s_addc_u32 s23, s27, 0
	s_sub_u32 s98, s20, 0x4000
	s_subb_u32 s99, s21, 0
	s_mov_b32 m0, s43
	s_nop 0
	global_load_lds_dwordx4 v144, s[98:99]
	s_mov_b32 m0, s44
	s_nop 0
	global_load_lds_dwordx4 v140, s[98:99]
	s_add_i32 m0, s36, 0xc000
	ds_read_b128 v[196:199], v171
	ds_read_b128 v[200:203], v171 offset:1024
	ds_read_b128 v[204:207], v171 offset:2048
	ds_read_b128 v[208:211], v171 offset:3072
	ds_read_b128 v[212:215], v171 offset:4096
	ds_read_b128 v[216:219], v171 offset:5120
	ds_read_b128 v[220:223], v171 offset:6144
	ds_read_b128 v[224:227], v171 offset:7168
	global_load_lds_dwordx4 v148, s[20:21]
	s_add_i32 m0, s36, 0xe000
	s_nop 0
	global_load_lds_dwordx4 v150, s[20:21]
	s_waitcnt vmcnt(8)
	s_waitcnt lgkmcnt(0)
	s_barrier
	s_setprio 1
	s_waitcnt lgkmcnt(0)
	v_mfma_i32_16x16x64_i8 v[134:137], v[90:93], v[196:199], v[134:137]
	v_mfma_i32_16x16x64_i8 v[130:133], v[172:175], v[196:199], v[130:133]
	v_mfma_i32_16x16x64_i8 v[118:121], v[90:93], v[204:207], v[118:121]
	v_mfma_i32_16x16x64_i8 v[114:117], v[172:175], v[204:207], v[114:117]
	v_mfma_i32_16x16x64_i8 v[102:105], v[90:93], v[212:215], v[102:105]
	v_mfma_i32_16x16x64_i8 v[94:97], v[172:175], v[212:215], v[94:97]
	v_mfma_i32_16x16x64_i8 v[78:81], v[90:93], v[220:223], v[78:81]
	v_mfma_i32_16x16x64_i8 v[74:77], v[172:175], v[220:223], v[74:77]
	v_mfma_i32_16x16x64_i8 v[134:137], v[98:101], v[200:203], v[134:137]
	v_mfma_i32_16x16x64_i8 v[130:133], v[176:179], v[200:203], v[130:133]
	v_mfma_i32_16x16x64_i8 v[118:121], v[98:101], v[208:211], v[118:121]
	v_mfma_i32_16x16x64_i8 v[114:117], v[176:179], v[208:211], v[114:117]
	v_mfma_i32_16x16x64_i8 v[102:105], v[98:101], v[216:219], v[102:105]
	v_mfma_i32_16x16x64_i8 v[94:97], v[176:179], v[216:219], v[94:97]
	v_mfma_i32_16x16x64_i8 v[78:81], v[98:101], v[224:227], v[78:81]
	v_mfma_i32_16x16x64_i8 v[74:77], v[176:179], v[224:227], v[74:77]
	v_mfma_i32_16x16x64_i8 v[126:129], v[180:183], v[196:199], v[126:129]
	v_mfma_i32_16x16x64_i8 v[122:125], v[188:191], v[196:199], v[122:125]
	v_mfma_i32_16x16x64_i8 v[110:113], v[180:183], v[204:207], v[110:113]
	v_mfma_i32_16x16x64_i8 v[106:109], v[188:191], v[204:207], v[106:109]
	v_mfma_i32_16x16x64_i8 v[86:89], v[180:183], v[212:215], v[86:89]
	v_mfma_i32_16x16x64_i8 v[82:85], v[188:191], v[212:215], v[82:85]
	v_mfma_i32_16x16x64_i8 v[70:73], v[180:183], v[220:223], v[70:73]
	v_mfma_i32_16x16x64_i8 v[66:69], v[188:191], v[220:223], v[66:69]
	v_mfma_i32_16x16x64_i8 v[126:129], v[184:187], v[200:203], v[126:129]
	v_mfma_i32_16x16x64_i8 v[122:125], v[192:195], v[200:203], v[122:125]
	v_mfma_i32_16x16x64_i8 v[110:113], v[184:187], v[208:211], v[110:113]
	v_mfma_i32_16x16x64_i8 v[106:109], v[192:195], v[208:211], v[106:109]
	v_mfma_i32_16x16x64_i8 v[86:89], v[184:187], v[216:219], v[86:89]
	v_mfma_i32_16x16x64_i8 v[82:85], v[192:195], v[216:219], v[82:85]
	v_mfma_i32_16x16x64_i8 v[70:73], v[184:187], v[224:227], v[70:73]
	v_mfma_i32_16x16x64_i8 v[66:69], v[192:195], v[224:227], v[66:69]
	s_setprio 0
	s_barrier
	s_add_i32 s54, s46, s33
	s_mov_b32 m0, s54
	ds_read_b128 v[196:199], v171 offset:16384
	ds_read_b128 v[200:203], v171 offset:17408
	ds_read_b128 v[204:207], v171 offset:18432
	ds_read_b128 v[208:211], v171 offset:19456
	ds_read_b128 v[212:215], v171 offset:20480
	ds_read_b128 v[216:219], v171 offset:21504
	ds_read_b128 v[220:223], v171 offset:22528
	ds_read_b128 v[224:227], v171 offset:23552
	global_load_lds_dwordx4 v142, s[24:25]
	s_add_i32 m0, s54, 0x2000
	s_add_u32 s54, s24, 0x4000
	s_addc_u32 s55, s25, 0
	s_add_i32 s56, s47, s33
	global_load_lds_dwordx4 v138, s[24:25]
	s_mov_b32 m0, s56
	s_nop 0
	global_load_lds_dwordx4 v142, s[54:55]
	s_add_i32 m0, s56, 0x2000
	s_nop 0
	global_load_lds_dwordx4 v138, s[54:55]
	s_waitcnt vmcnt(6)
	s_waitcnt lgkmcnt(0)
	s_barrier
	s_setprio 1
	s_waitcnt lgkmcnt(0)
	v_mfma_i32_16x16x64_i8 v[62:65], v[90:93], v[196:199], v[62:65]
	v_mfma_i32_16x16x64_i8 v[58:61], v[172:175], v[196:199], v[58:61]
	v_mfma_i32_16x16x64_i8 v[46:49], v[90:93], v[204:207], v[46:49]
	v_mfma_i32_16x16x64_i8 v[42:45], v[172:175], v[204:207], v[42:45]
	v_mfma_i32_16x16x64_i8 v[30:33], v[90:93], v[212:215], v[30:33]
	v_mfma_i32_16x16x64_i8 v[26:29], v[172:175], v[212:215], v[26:29]
	v_mfma_i32_16x16x64_i8 v[14:17], v[90:93], v[220:223], v[14:17]
	v_mfma_i32_16x16x64_i8 v[10:13], v[172:175], v[220:223], v[10:13]
	v_mfma_i32_16x16x64_i8 v[62:65], v[98:101], v[200:203], v[62:65]
	v_mfma_i32_16x16x64_i8 v[58:61], v[176:179], v[200:203], v[58:61]
	v_mfma_i32_16x16x64_i8 v[46:49], v[98:101], v[208:211], v[46:49]
	v_mfma_i32_16x16x64_i8 v[42:45], v[176:179], v[208:211], v[42:45]
	v_mfma_i32_16x16x64_i8 v[30:33], v[98:101], v[216:219], v[30:33]
	v_mfma_i32_16x16x64_i8 v[26:29], v[176:179], v[216:219], v[26:29]
	v_mfma_i32_16x16x64_i8 v[14:17], v[98:101], v[224:227], v[14:17]
	v_mfma_i32_16x16x64_i8 v[10:13], v[176:179], v[224:227], v[10:13]
	v_mfma_i32_16x16x64_i8 v[54:57], v[180:183], v[196:199], v[54:57]
	v_mfma_i32_16x16x64_i8 v[50:53], v[188:191], v[196:199], v[50:53]
	v_mfma_i32_16x16x64_i8 v[38:41], v[180:183], v[204:207], v[38:41]
	v_mfma_i32_16x16x64_i8 v[34:37], v[188:191], v[204:207], v[34:37]
	v_mfma_i32_16x16x64_i8 v[22:25], v[180:183], v[212:215], v[22:25]
	v_mfma_i32_16x16x64_i8 v[18:21], v[188:191], v[212:215], v[18:21]
	v_mfma_i32_16x16x64_i8 v[6:9], v[180:183], v[220:223], v[6:9]
	v_mfma_i32_16x16x64_i8 v[2:5], v[188:191], v[220:223], v[2:5]
	v_mfma_i32_16x16x64_i8 v[54:57], v[184:187], v[200:203], v[54:57]
	v_mfma_i32_16x16x64_i8 v[50:53], v[192:195], v[200:203], v[50:53]
	v_mfma_i32_16x16x64_i8 v[38:41], v[184:187], v[208:211], v[38:41]
	v_mfma_i32_16x16x64_i8 v[34:37], v[192:195], v[208:211], v[34:37]
	v_mfma_i32_16x16x64_i8 v[22:25], v[184:187], v[216:219], v[22:25]
	v_mfma_i32_16x16x64_i8 v[18:21], v[192:195], v[216:219], v[18:21]
	v_mfma_i32_16x16x64_i8 v[6:9], v[184:187], v[224:227], v[6:9]
	v_mfma_i32_16x16x64_i8 v[2:5], v[192:195], v[224:227], v[2:5]
	s_setprio 0
	s_barrier
; #define PG8_STAGE(bufoff, gbase, voff) do { _Pragma("unroll") for (int _i = 0; _i < 2; ++_i) \
;         __builtin_amdgcn_global_load_lds((const unsigned*)((const char*)(gbase) + (voff)[_i]), (LAS unsigned*)(lds + (bufoff) + ldsw + _i * 8192), 16, 0, 0); } while (0)
; #define PG8_LDA(dst, b, h) do { _Pragma("unroll") for (int m = 0; m < 4; ++m) _Pragma("unroll") for (int k = 0; k < 2; ++k) dst[m][k] = *(const LAS bf16x8*)(lds + PG8_SA(b, h) + aoff + m * 2048 + k * 1024); } while (0)
; #define PG8_LDB(dst, b, h) do { _Pragma("unroll") for (int n = 0; n < 2; ++n) _Pragma("unroll") for (int k = 0; k < 2; ++k) dst[n][k] = *(const LAS bf16x8*)(lds + PG8_SB(b, h) + boff + n * 2048 + k * 1024); } while (0)
; #define PG8_WAIT_V(n) asm volatile("s_waitcnt vmcnt(" #n ")" ::: "memory")
; #define PG8_WAIT_L(n) asm volatile("s_waitcnt lgkmcnt(" #n ")" ::: "memory")
; #define PG8_BAR __builtin_amdgcn_s_barrier()
; #define PG8_SCHED __builtin_amdgcn_sched_barrier(0)
; template <class Epi, class Sched, bool I8 = false>
; __device__ __forceinline__ void gemm_phase(LAS unsigned char* lds, const Gemm g, const Sched& S, const Epi& E) {
;     ...
;             PG8_LDB(B0, 1, 0); PG8_LDB(B1, 1, 1); PG8_SCHED; PG8_LDA(At, 1, 0); PG8_STAGE(PG8_SA(0, 1), a2 + hstepA, voffA);
;             PG8_WAIT_V(8); PG8_WAIT_L(0); PG8_BAR; PG8_MMA(0, 0, At, B0); PG8_MMA(0, 1, At, B1); PG8_BAR; PG8_SCHED;
;             PG8_LDA(At, 1, 1); PG8_STAGE(PG8_SB(1, 0), b3, voffB); PG8_STAGE(PG8_SB(1, 1), b3 + hstepB, voffB); PG8_STAGE(PG8_SA(1, 0), a3, voffA);
;             PG8_WAIT_V(8); PG8_WAIT_L(0); PG8_BAR; PG8_MMA(1, 0, At, B0); PG8_MMA(1, 1, At, B1); PG8_BAR; PG8_SCHED;
;         }
;         if (wr == 0) PG8_BAR;
	s_add_i32 s54, 0, 0x18000
	v_add_u32_e32 v146, s54, v165
	s_add_i32 s55, 0, 0x1c000
	ds_read_b128 v[90:93], v146
	ds_read_b128 v[98:101], v146 offset:1024
	ds_read_b128 v[172:175], v146 offset:2048
	ds_read_b128 v[176:179], v146 offset:3072
	v_add_u32_e32 v146, s55, v165
	ds_read_b128 v[180:183], v146
	ds_read_b128 v[184:187], v146 offset:1024
	ds_read_b128 v[188:191], v146 offset:2048
	ds_read_b128 v[192:195], v146 offset:3072
	s_mov_b32 m0, s36
	s_nop 0
	global_load_lds_dwordx4 v144, s[26:27]
	s_mov_b32 m0, s37
	s_nop 0
	global_load_lds_dwordx4 v140, s[26:27]
	s_add_u32 s26, s26, 0x4000
	s_addc_u32 s27, s27, 0
	s_mov_b32 m0, s38
	ds_read_b128 v[196:199], v171 offset:32768
	ds_read_b128 v[200:203], v171 offset:33792
	ds_read_b128 v[204:207], v171 offset:34816
	ds_read_b128 v[208:211], v171 offset:35840
	ds_read_b128 v[212:215], v171 offset:36864
	ds_read_b128 v[216:219], v171 offset:37888
	ds_read_b128 v[220:223], v171 offset:38912
	ds_read_b128 v[224:227], v171 offset:39936
	global_load_lds_dwordx4 v144, s[26:27]
	s_mov_b32 m0, s39
	s_nop 0
	global_load_lds_dwordx4 v140, s[26:27]
	s_waitcnt vmcnt(8)
	s_waitcnt lgkmcnt(0)
	s_barrier
	s_setprio 1
	s_waitcnt lgkmcnt(0)
	v_mfma_i32_16x16x64_i8 v[134:137], v[90:93], v[196:199], v[134:137]
	v_mfma_i32_16x16x64_i8 v[130:133], v[172:175], v[196:199], v[130:133]
	v_mfma_i32_16x16x64_i8 v[118:121], v[90:93], v[204:207], v[118:121]
	v_mfma_i32_16x16x64_i8 v[114:117], v[172:175], v[204:207], v[114:117]
	v_mfma_i32_16x16x64_i8 v[102:105], v[90:93], v[212:215], v[102:105]
	v_mfma_i32_16x16x64_i8 v[94:97], v[172:175], v[212:215], v[94:97]
	v_mfma_i32_16x16x64_i8 v[78:81], v[90:93], v[220:223], v[78:81]
	v_mfma_i32_16x16x64_i8 v[74:77], v[172:175], v[220:223], v[74:77]
	v_mfma_i32_16x16x64_i8 v[134:137], v[98:101], v[200:203], v[134:137]
	v_mfma_i32_16x16x64_i8 v[130:133], v[176:179], v[200:203], v[130:133]
	v_mfma_i32_16x16x64_i8 v[118:121], v[98:101], v[208:211], v[118:121]
	v_mfma_i32_16x16x64_i8 v[114:117], v[176:179], v[208:211], v[114:117]
	v_mfma_i32_16x16x64_i8 v[102:105], v[98:101], v[216:219], v[102:105]
	v_mfma_i32_16x16x64_i8 v[94:97], v[176:179], v[216:219], v[94:97]
	v_mfma_i32_16x16x64_i8 v[78:81], v[98:101], v[224:227], v[78:81]
	v_mfma_i32_16x16x64_i8 v[74:77], v[176:179], v[224:227], v[74:77]
	v_mfma_i32_16x16x64_i8 v[126:129], v[180:183], v[196:199], v[126:129]
	v_mfma_i32_16x16x64_i8 v[122:125], v[188:191], v[196:199], v[122:125]
	v_mfma_i32_16x16x64_i8 v[110:113], v[180:183], v[204:207], v[110:113]
	v_mfma_i32_16x16x64_i8 v[106:109], v[188:191], v[204:207], v[106:109]
	v_mfma_i32_16x16x64_i8 v[86:89], v[180:183], v[212:215], v[86:89]
	v_mfma_i32_16x16x64_i8 v[82:85], v[188:191], v[212:215], v[82:85]
	v_mfma_i32_16x16x64_i8 v[70:73], v[180:183], v[220:223], v[70:73]
	v_mfma_i32_16x16x64_i8 v[66:69], v[188:191], v[220:223], v[66:69]
	v_mfma_i32_16x16x64_i8 v[126:129], v[184:187], v[200:203], v[126:129]
	v_mfma_i32_16x16x64_i8 v[122:125], v[192:195], v[200:203], v[122:125]
	v_mfma_i32_16x16x64_i8 v[110:113], v[184:187], v[208:211], v[110:113]
	v_mfma_i32_16x16x64_i8 v[106:109], v[192:195], v[208:211], v[106:109]
	v_mfma_i32_16x16x64_i8 v[86:89], v[184:187], v[216:219], v[86:89]
	v_mfma_i32_16x16x64_i8 v[82:85], v[192:195], v[216:219], v[82:85]
	v_mfma_i32_16x16x64_i8 v[70:73], v[184:187], v[224:227], v[70:73]
	v_mfma_i32_16x16x64_i8 v[66:69], v[192:195], v[224:227], v[66:69]
	s_setprio 0
	s_barrier
	s_add_u32 s26, s24, 0x8000
	s_addc_u32 s27, s25, 0
	s_add_i32 s54, s54, s33
	s_mov_b32 m0, s54
	ds_read_b128 v[196:199], v171 offset:49152
	ds_read_b128 v[200:203], v171 offset:50176
	ds_read_b128 v[204:207], v171 offset:51200
	ds_read_b128 v[208:211], v171 offset:52224
	ds_read_b128 v[212:215], v171 offset:53248
	ds_read_b128 v[216:219], v171 offset:54272
	ds_read_b128 v[220:223], v171 offset:55296
	ds_read_b128 v[224:227], v171 offset:56320
	global_load_lds_dwordx4 v142, s[26:27]
	s_add_i32 m0, s54, 0x2000
	s_add_u32 s24, s24, 0xc000
	v_lshl_add_u64 v[158:159], s[26:27], 0, v[138:139]
	s_addc_u32 s25, s25, 0
	s_add_i32 s26, s55, s33
	global_load_lds_dwordx4 v[158:159], off
	s_mov_b32 m0, s26
	s_nop 0
	global_load_lds_dwordx4 v142, s[24:25]
	s_add_i32 m0, s26, 0x2000
	s_nop 0
	global_load_lds_dwordx4 v138, s[24:25]
	s_waitcnt vmcnt(6)
	s_waitcnt lgkmcnt(0)
	s_barrier
	s_setprio 1
	s_waitcnt lgkmcnt(0)
	v_mfma_i32_16x16x64_i8 v[62:65], v[90:93], v[196:199], v[62:65]
	v_mfma_i32_16x16x64_i8 v[58:61], v[172:175], v[196:199], v[58:61]
	v_mfma_i32_16x16x64_i8 v[46:49], v[90:93], v[204:207], v[46:49]
	v_mfma_i32_16x16x64_i8 v[42:45], v[172:175], v[204:207], v[42:45]
	v_mfma_i32_16x16x64_i8 v[30:33], v[90:93], v[212:215], v[30:33]
	v_mfma_i32_16x16x64_i8 v[26:29], v[172:175], v[212:215], v[26:29]
	v_mfma_i32_16x16x64_i8 v[14:17], v[90:93], v[220:223], v[14:17]
	v_mfma_i32_16x16x64_i8 v[10:13], v[172:175], v[220:223], v[10:13]
	v_mfma_i32_16x16x64_i8 v[62:65], v[98:101], v[200:203], v[62:65]
	v_mfma_i32_16x16x64_i8 v[58:61], v[176:179], v[200:203], v[58:61]
	v_mfma_i32_16x16x64_i8 v[46:49], v[98:101], v[208:211], v[46:49]
	v_mfma_i32_16x16x64_i8 v[42:45], v[176:179], v[208:211], v[42:45]
	v_mfma_i32_16x16x64_i8 v[30:33], v[98:101], v[216:219], v[30:33]
	v_mfma_i32_16x16x64_i8 v[26:29], v[176:179], v[216:219], v[26:29]
	v_mfma_i32_16x16x64_i8 v[14:17], v[98:101], v[224:227], v[14:17]
	v_mfma_i32_16x16x64_i8 v[10:13], v[176:179], v[224:227], v[10:13]
	v_mfma_i32_16x16x64_i8 v[54:57], v[180:183], v[196:199], v[54:57]
	v_mfma_i32_16x16x64_i8 v[50:53], v[188:191], v[196:199], v[50:53]
	v_mfma_i32_16x16x64_i8 v[38:41], v[180:183], v[204:207], v[38:41]
	v_mfma_i32_16x16x64_i8 v[34:37], v[188:191], v[204:207], v[34:37]
	v_mfma_i32_16x16x64_i8 v[22:25], v[180:183], v[212:215], v[22:25]
	v_mfma_i32_16x16x64_i8 v[18:21], v[188:191], v[212:215], v[18:21]
	v_mfma_i32_16x16x64_i8 v[6:9], v[180:183], v[220:223], v[6:9]
	v_mfma_i32_16x16x64_i8 v[2:5], v[188:191], v[220:223], v[2:5]
	v_mfma_i32_16x16x64_i8 v[54:57], v[184:187], v[200:203], v[54:57]
	v_mfma_i32_16x16x64_i8 v[50:53], v[192:195], v[200:203], v[50:53]
	v_mfma_i32_16x16x64_i8 v[38:41], v[184:187], v[208:211], v[38:41]
	v_mfma_i32_16x16x64_i8 v[34:37], v[192:195], v[208:211], v[34:37]
	v_mfma_i32_16x16x64_i8 v[22:25], v[184:187], v[216:219], v[22:25]
	v_mfma_i32_16x16x64_i8 v[18:21], v[192:195], v[216:219], v[18:21]
	v_mfma_i32_16x16x64_i8 v[6:9], v[184:187], v[224:227], v[6:9]
	v_mfma_i32_16x16x64_i8 v[2:5], v[192:195], v[224:227], v[2:5]
	s_setprio 0
	s_barrier
	s_add_i32 s53, s53, 2
	s_add_u32 s20, s20, 0x10000
	s_addc_u32 s21, s21, 0
	s_add_u32 s51, s51, 0x10000
	s_addc_u32 s52, s52, 0
	s_cmp_gt_u32 s53, 29
	s_cbranch_scc0 .LBB0_1169
	s_and_b64 vcc, exec, s[8:9]
	s_cbranch_vccz .LBB0_1172
	s_barrier

; #define PG8_STAGE(bufoff, gbase, voff) do { _Pragma("unroll") for (int _i = 0; _i < 2; ++_i) \
;         __builtin_amdgcn_global_load_lds((const unsigned*)((const char*)(gbase) + (voff)[_i]), (LAS unsigned*)(lds + (bufoff) + ldsw + _i * 8192), 16, 0, 0); } while (0)
; #define PG8_LDA(dst, b, h) do { _Pragma("unroll") for (int m = 0; m < 4; ++m) _Pragma("unroll") for (int k = 0; k < 2; ++k) dst[m][k] = *(const LAS bf16x8*)(lds + PG8_SA(b, h) + aoff + m * 2048 + k * 1024); } while (0)
; #define PG8_LDB(dst, b, h) do { _Pragma("unroll") for (int n = 0; n < 2; ++n) _Pragma("unroll") for (int k = 0; k < 2; ++k) dst[n][k] = *(const LAS bf16x8*)(lds + PG8_SB(b, h) + boff + n * 2048 + k * 1024); } while (0)
; #define PG8_WAIT_V(n) asm volatile("s_waitcnt vmcnt(" #n ")" ::: "memory")
; #define PG8_WAIT_L(n) asm volatile("s_waitcnt lgkmcnt(" #n ")" ::: "memory")
; #define PG8_BAR __builtin_amdgcn_s_barrier()
; #define PG8_SCHED __builtin_amdgcn_sched_barrier(0)
; template <class Epi, class Sched, bool I8 = false>
; __device__ __forceinline__ void gemm_phase(LAS unsigned char* lds, const Gemm g, const Sched& S, const Epi& E) {
;     ...
;         for (int t = 0; t < nt; t += 2) {
;             const bool last = (t == nt - 2);
;             const char* a1 = cA + (size_t)(t + 1) * kstep;
;             const char* a2 = last ? nA : cA + (size_t)(t + 2) * kstep; const char* b2 = last ? nB : cB + (size_t)(t + 2) * kstep;
;             const char* a3 = a2 + kstep; const char* b3 = b2 + kstep;
;             PG8_LDB(B0, 0, 0); PG8_LDB(B1, 0, 1); PG8_SCHED; PG8_LDA(At, 0, 0); PG8_STAGE(PG8_SA(1, 1), a1 + hstepA, voffA);
;             PG8_WAIT_V(8); PG8_WAIT_L(0); PG8_BAR; PG8_MMA(0, 0, At, B0); PG8_MMA(0, 1, At, B1); PG8_BAR; PG8_SCHED;
;             PG8_LDA(At, 0, 1); PG8_STAGE(PG8_SB(0, 0), b2, voffB); PG8_STAGE(PG8_SB(0, 1), b2 + hstepB, voffB); PG8_STAGE(PG8_SA(0, 0), a2, voffA);
;             PG8_WAIT_V(8); PG8_WAIT_L(0); PG8_BAR; PG8_MMA(1, 0, At, B0); PG8_MMA(1, 1, At, B1); PG8_BAR; PG8_SCHED;
.LBB0_1393:
	ds_read_b128 v[66:69], v180
	ds_read_b128 v[70:73], v180 offset:1024
	ds_read_b128 v[74:77], v180 offset:2048
	ds_read_b128 v[78:81], v180 offset:3072
	ds_read_b128 v[146:149], v181
	ds_read_b128 v[150:153], v181 offset:1024
	ds_read_b128 v[174:177], v181 offset:2048
	ds_read_b128 v[184:187], v181 offset:3072
	s_add_u32 s20, s18, 0x4000
	s_addc_u32 s21, s19, 0
	s_cmpk_eq_i32 s49, 0x52
	s_cselect_b32 s24, s0, s20
	s_cselect_b32 s25, s1, s21
	s_cselect_b32 s22, s16, s47
	s_cselect_b32 s23, s17, s48
	s_add_u32 s20, s24, 0x8000
	s_addc_u32 s21, s25, 0
	s_sub_u32 s98, s18, 0x4000
	s_subb_u32 s99, s19, 0
	s_mov_b32 m0, s37
	s_nop 0
	global_load_lds_dwordx4 v156, s[98:99]
	s_mov_b32 m0, s38
	s_nop 0
	global_load_lds_dwordx4 v160, s[98:99]
	s_add_i32 m0, s31, 0xc000
	ds_read_b128 v[188:191], v182
	ds_read_b128 v[192:195], v182 offset:1024
	ds_read_b128 v[196:199], v182 offset:2048
	ds_read_b128 v[200:203], v182 offset:3072
	ds_read_b128 v[204:207], v182 offset:4096
	ds_read_b128 v[208:211], v182 offset:5120
	ds_read_b128 v[212:215], v182 offset:6144
	ds_read_b128 v[216:219], v182 offset:7168
	global_load_lds_dwordx4 v166, s[18:19]
	s_add_i32 m0, s31, 0xe000
	s_nop 0
	global_load_lds_dwordx4 v168, s[18:19]
	s_waitcnt vmcnt(8)
	s_waitcnt lgkmcnt(0)
	s_barrier
	s_setprio 1
	s_waitcnt lgkmcnt(0)
	v_mfma_i32_16x16x64_i8 v[142:145], v[66:69], v[188:191], v[142:145]
	v_mfma_i32_16x16x64_i8 v[138:141], v[74:77], v[188:191], v[138:141]
	v_mfma_i32_16x16x64_i8 v[126:129], v[66:69], v[196:199], v[126:129]
	v_mfma_i32_16x16x64_i8 v[122:125], v[74:77], v[196:199], v[122:125]
	v_mfma_i32_16x16x64_i8 v[110:113], v[66:69], v[204:207], v[110:113]
	v_mfma_i32_16x16x64_i8 v[106:109], v[74:77], v[204:207], v[106:109]
	v_mfma_i32_16x16x64_i8 v[94:97], v[66:69], v[212:215], v[94:97]
	v_mfma_i32_16x16x64_i8 v[90:93], v[74:77], v[212:215], v[90:93]
	v_mfma_i32_16x16x64_i8 v[142:145], v[70:73], v[192:195], v[142:145]
	v_mfma_i32_16x16x64_i8 v[138:141], v[78:81], v[192:195], v[138:141]
	v_mfma_i32_16x16x64_i8 v[126:129], v[70:73], v[200:203], v[126:129]
	v_mfma_i32_16x16x64_i8 v[122:125], v[78:81], v[200:203], v[122:125]
	v_mfma_i32_16x16x64_i8 v[110:113], v[70:73], v[208:211], v[110:113]
	v_mfma_i32_16x16x64_i8 v[106:109], v[78:81], v[208:211], v[106:109]
	v_mfma_i32_16x16x64_i8 v[94:97], v[70:73], v[216:219], v[94:97]
	v_mfma_i32_16x16x64_i8 v[90:93], v[78:81], v[216:219], v[90:93]
	v_mfma_i32_16x16x64_i8 v[134:137], v[146:149], v[188:191], v[134:137]
	v_mfma_i32_16x16x64_i8 v[130:133], v[174:177], v[188:191], v[130:133]
	v_mfma_i32_16x16x64_i8 v[118:121], v[146:149], v[196:199], v[118:121]
	v_mfma_i32_16x16x64_i8 v[114:117], v[174:177], v[196:199], v[114:117]
	v_mfma_i32_16x16x64_i8 v[102:105], v[146:149], v[204:207], v[102:105]
	v_mfma_i32_16x16x64_i8 v[98:101], v[174:177], v[204:207], v[98:101]
	v_mfma_i32_16x16x64_i8 v[86:89], v[146:149], v[212:215], v[86:89]
	v_mfma_i32_16x16x64_i8 v[82:85], v[174:177], v[212:215], v[82:85]
	v_mfma_i32_16x16x64_i8 v[134:137], v[150:153], v[192:195], v[134:137]
	v_mfma_i32_16x16x64_i8 v[130:133], v[184:187], v[192:195], v[130:133]
	v_mfma_i32_16x16x64_i8 v[118:121], v[150:153], v[200:203], v[118:121]
	v_mfma_i32_16x16x64_i8 v[114:117], v[184:187], v[200:203], v[114:117]
	v_mfma_i32_16x16x64_i8 v[102:105], v[150:153], v[208:211], v[102:105]
	v_mfma_i32_16x16x64_i8 v[98:101], v[184:187], v[208:211], v[98:101]
	v_mfma_i32_16x16x64_i8 v[86:89], v[150:153], v[216:219], v[86:89]
	v_mfma_i32_16x16x64_i8 v[82:85], v[184:187], v[216:219], v[82:85]
	s_setprio 0
	s_barrier
	s_add_i32 s50, s41, s30
	s_mov_b32 m0, s50
	ds_read_b128 v[188:191], v182 offset:16384
	ds_read_b128 v[192:195], v182 offset:17408
	ds_read_b128 v[196:199], v182 offset:18432
	ds_read_b128 v[200:203], v182 offset:19456
	ds_read_b128 v[204:207], v182 offset:20480
	ds_read_b128 v[208:211], v182 offset:21504
	ds_read_b128 v[212:215], v182 offset:22528
	ds_read_b128 v[216:219], v182 offset:23552
	global_load_lds_dwordx4 v158, s[22:23]
	s_add_i32 m0, s50, 0x2000
	s_add_u32 s50, s22, 0x4000
	s_addc_u32 s51, s23, 0
	s_add_i32 s52, s42, s30
	global_load_lds_dwordx4 v162, s[22:23]
	s_mov_b32 m0, s52
	s_nop 0
	global_load_lds_dwordx4 v158, s[50:51]
	s_add_i32 m0, s52, 0x2000
	s_nop 0
	global_load_lds_dwordx4 v162, s[50:51]
	s_waitcnt vmcnt(6)
	s_waitcnt lgkmcnt(0)
	s_barrier
	s_setprio 1
	s_waitcnt lgkmcnt(0)
	v_mfma_i32_16x16x64_i8 v[62:65], v[66:69], v[188:191], v[62:65]
	v_mfma_i32_16x16x64_i8 v[58:61], v[74:77], v[188:191], v[58:61]
	v_mfma_i32_16x16x64_i8 v[46:49], v[66:69], v[196:199], v[46:49]
	v_mfma_i32_16x16x64_i8 v[42:45], v[74:77], v[196:199], v[42:45]
	v_mfma_i32_16x16x64_i8 v[30:33], v[66:69], v[204:207], v[30:33]
	v_mfma_i32_16x16x64_i8 v[26:29], v[74:77], v[204:207], v[26:29]
	v_mfma_i32_16x16x64_i8 v[14:17], v[66:69], v[212:215], v[14:17]
	v_mfma_i32_16x16x64_i8 v[10:13], v[74:77], v[212:215], v[10:13]
	v_mfma_i32_16x16x64_i8 v[62:65], v[70:73], v[192:195], v[62:65]
	v_mfma_i32_16x16x64_i8 v[58:61], v[78:81], v[192:195], v[58:61]
	v_mfma_i32_16x16x64_i8 v[46:49], v[70:73], v[200:203], v[46:49]
	v_mfma_i32_16x16x64_i8 v[42:45], v[78:81], v[200:203], v[42:45]
	v_mfma_i32_16x16x64_i8 v[30:33], v[70:73], v[208:211], v[30:33]
	v_mfma_i32_16x16x64_i8 v[26:29], v[78:81], v[208:211], v[26:29]
	v_mfma_i32_16x16x64_i8 v[14:17], v[70:73], v[216:219], v[14:17]
	v_mfma_i32_16x16x64_i8 v[10:13], v[78:81], v[216:219], v[10:13]
	v_mfma_i32_16x16x64_i8 v[54:57], v[146:149], v[188:191], v[54:57]
	v_mfma_i32_16x16x64_i8 v[50:53], v[174:177], v[188:191], v[50:53]
	v_mfma_i32_16x16x64_i8 v[38:41], v[146:149], v[196:199], v[38:41]
	v_mfma_i32_16x16x64_i8 v[34:37], v[174:177], v[196:199], v[34:37]
	v_mfma_i32_16x16x64_i8 v[22:25], v[146:149], v[204:207], v[22:25]
	v_mfma_i32_16x16x64_i8 v[18:21], v[174:177], v[204:207], v[18:21]
	v_mfma_i32_16x16x64_i8 v[6:9], v[146:149], v[212:215], v[6:9]
	v_mfma_i32_16x16x64_i8 v[2:5], v[174:177], v[212:215], v[2:5]
	v_mfma_i32_16x16x64_i8 v[54:57], v[150:153], v[192:195], v[54:57]
	v_mfma_i32_16x16x64_i8 v[50:53], v[184:187], v[192:195], v[50:53]
	v_mfma_i32_16x16x64_i8 v[38:41], v[150:153], v[200:203], v[38:41]
	v_mfma_i32_16x16x64_i8 v[34:37], v[184:187], v[200:203], v[34:37]
	v_mfma_i32_16x16x64_i8 v[22:25], v[150:153], v[208:211], v[22:25]
	v_mfma_i32_16x16x64_i8 v[18:21], v[184:187], v[208:211], v[18:21]
	v_mfma_i32_16x16x64_i8 v[6:9], v[150:153], v[216:219], v[6:9]
	v_mfma_i32_16x16x64_i8 v[2:5], v[184:187], v[216:219], v[2:5]
	s_setprio 0
	s_barrier
; #define PG8_STAGE(bufoff, gbase, voff) do { _Pragma("unroll") for (int _i = 0; _i < 2; ++_i) \
;         __builtin_amdgcn_global_load_lds((const unsigned*)((const char*)(gbase) + (voff)[_i]), (LAS unsigned*)(lds + (bufoff) + ldsw + _i * 8192), 16, 0, 0); } while (0)
; #define PG8_LDA(dst, b, h) do { _Pragma("unroll") for (int m = 0; m < 4; ++m) _Pragma("unroll") for (int k = 0; k < 2; ++k) dst[m][k] = *(const LAS bf16x8*)(lds + PG8_SA(b, h) + aoff + m * 2048 + k * 1024); } while (0)
; #define PG8_LDB(dst, b, h) do { _Pragma("unroll") for (int n = 0; n < 2; ++n) _Pragma("unroll") for (int k = 0; k < 2; ++k) dst[n][k] = *(const LAS bf16x8*)(lds + PG8_SB(b, h) + boff + n * 2048 + k * 1024); } while (0)
; #define PG8_WAIT_V(n) asm volatile("s_waitcnt vmcnt(" #n ")" ::: "memory")
; #define PG8_WAIT_L(n) asm volatile("s_waitcnt lgkmcnt(" #n ")" ::: "memory")
; #define PG8_BAR __builtin_amdgcn_s_barrier()
; #define PG8_SCHED __builtin_amdgcn_sched_barrier(0)
; template <class Epi, class Sched, bool I8 = false>
; __device__ __forceinline__ void gemm_phase(LAS unsigned char* lds, const Gemm g, const Sched& S, const Epi& E) {
;     ...
;             PG8_LDB(B0, 1, 0); PG8_LDB(B1, 1, 1); PG8_SCHED; PG8_LDA(At, 1, 0); PG8_STAGE(PG8_SA(0, 1), a2 + hstepA, voffA);
;             PG8_WAIT_V(8); PG8_WAIT_L(0); PG8_BAR; PG8_MMA(0, 0, At, B0); PG8_MMA(0, 1, At, B1); PG8_BAR; PG8_SCHED;
;             PG8_LDA(At, 1, 1); PG8_STAGE(PG8_SB(1, 0), b3, voffB); PG8_STAGE(PG8_SB(1, 1), b3 + hstepB, voffB); PG8_STAGE(PG8_SA(1, 0), a3, voffA);
;             PG8_WAIT_V(8); PG8_WAIT_L(0); PG8_BAR; PG8_MMA(1, 0, At, B0); PG8_MMA(1, 1, At, B1); PG8_BAR; PG8_SCHED;
;         }
;         if (wr == 0) PG8_BAR;
	s_add_i32 s50, 0, 0x18000
	s_add_i32 s51, 0, 0x1c000
	v_add_u32_e32 v78, s50, v178
	v_add_u32_e32 v164, s51, v178
	ds_read_b128 v[66:69], v78
	ds_read_b128 v[70:73], v78 offset:1024
	ds_read_b128 v[74:77], v78 offset:2048
	ds_read_b128 v[78:81], v78 offset:3072
	ds_read_b128 v[146:149], v164
	ds_read_b128 v[150:153], v164 offset:1024
	ds_read_b128 v[174:177], v164 offset:2048
	ds_read_b128 v[184:187], v164 offset:3072
	s_mov_b32 m0, s31
	s_nop 0
	global_load_lds_dwordx4 v156, s[24:25]
	s_mov_b32 m0, s33
	s_nop 0
	global_load_lds_dwordx4 v160, s[24:25]
	s_add_u32 s24, s24, 0x4000
	s_addc_u32 s25, s25, 0
	s_mov_b32 m0, s34
	ds_read_b128 v[188:191], v182 offset:32768
	ds_read_b128 v[192:195], v182 offset:33792
	ds_read_b128 v[196:199], v182 offset:34816
	ds_read_b128 v[200:203], v182 offset:35840
	ds_read_b128 v[204:207], v182 offset:36864
	ds_read_b128 v[208:211], v182 offset:37888
	ds_read_b128 v[212:215], v182 offset:38912
	ds_read_b128 v[216:219], v182 offset:39936
	global_load_lds_dwordx4 v156, s[24:25]
	s_mov_b32 m0, s35
	s_nop 0
	global_load_lds_dwordx4 v160, s[24:25]
	s_waitcnt vmcnt(8)
	s_waitcnt lgkmcnt(0)
	s_barrier
	s_setprio 1
	s_waitcnt lgkmcnt(0)
	v_mfma_i32_16x16x64_i8 v[142:145], v[66:69], v[188:191], v[142:145]
	v_mfma_i32_16x16x64_i8 v[138:141], v[74:77], v[188:191], v[138:141]
	v_mfma_i32_16x16x64_i8 v[126:129], v[66:69], v[196:199], v[126:129]
	v_mfma_i32_16x16x64_i8 v[122:125], v[74:77], v[196:199], v[122:125]
	v_mfma_i32_16x16x64_i8 v[110:113], v[66:69], v[204:207], v[110:113]
	v_mfma_i32_16x16x64_i8 v[106:109], v[74:77], v[204:207], v[106:109]
	v_mfma_i32_16x16x64_i8 v[94:97], v[66:69], v[212:215], v[94:97]
	v_mfma_i32_16x16x64_i8 v[90:93], v[74:77], v[212:215], v[90:93]
	v_mfma_i32_16x16x64_i8 v[142:145], v[70:73], v[192:195], v[142:145]
	v_mfma_i32_16x16x64_i8 v[138:141], v[78:81], v[192:195], v[138:141]
	v_mfma_i32_16x16x64_i8 v[126:129], v[70:73], v[200:203], v[126:129]
	v_mfma_i32_16x16x64_i8 v[122:125], v[78:81], v[200:203], v[122:125]
	v_mfma_i32_16x16x64_i8 v[110:113], v[70:73], v[208:211], v[110:113]
	v_mfma_i32_16x16x64_i8 v[106:109], v[78:81], v[208:211], v[106:109]
	v_mfma_i32_16x16x64_i8 v[94:97], v[70:73], v[216:219], v[94:97]
	v_mfma_i32_16x16x64_i8 v[90:93], v[78:81], v[216:219], v[90:93]
	v_mfma_i32_16x16x64_i8 v[134:137], v[146:149], v[188:191], v[134:137]
	v_mfma_i32_16x16x64_i8 v[130:133], v[174:177], v[188:191], v[130:133]
	v_mfma_i32_16x16x64_i8 v[118:121], v[146:149], v[196:199], v[118:121]
	v_mfma_i32_16x16x64_i8 v[114:117], v[174:177], v[196:199], v[114:117]
	v_mfma_i32_16x16x64_i8 v[102:105], v[146:149], v[204:207], v[102:105]
	v_mfma_i32_16x16x64_i8 v[98:101], v[174:177], v[204:207], v[98:101]
	v_mfma_i32_16x16x64_i8 v[86:89], v[146:149], v[212:215], v[86:89]
	v_mfma_i32_16x16x64_i8 v[82:85], v[174:177], v[212:215], v[82:85]
	v_mfma_i32_16x16x64_i8 v[134:137], v[150:153], v[192:195], v[134:137]
	v_mfma_i32_16x16x64_i8 v[130:133], v[184:187], v[192:195], v[130:133]
	v_mfma_i32_16x16x64_i8 v[118:121], v[150:153], v[200:203], v[118:121]
	v_mfma_i32_16x16x64_i8 v[114:117], v[184:187], v[200:203], v[114:117]
	v_mfma_i32_16x16x64_i8 v[102:105], v[150:153], v[208:211], v[102:105]
	v_mfma_i32_16x16x64_i8 v[98:101], v[184:187], v[208:211], v[98:101]
	v_mfma_i32_16x16x64_i8 v[86:89], v[150:153], v[216:219], v[86:89]
	v_mfma_i32_16x16x64_i8 v[82:85], v[184:187], v[216:219], v[82:85]
	s_setprio 0
	s_barrier
	s_add_u32 s24, s22, 0x8000
	s_addc_u32 s25, s23, 0
	s_add_i32 s50, s50, s30
	s_mov_b32 m0, s50
	ds_read_b128 v[188:191], v182 offset:49152
	ds_read_b128 v[192:195], v182 offset:50176
	ds_read_b128 v[196:199], v182 offset:51200
	ds_read_b128 v[200:203], v182 offset:52224
	ds_read_b128 v[204:207], v182 offset:53248
	ds_read_b128 v[208:211], v182 offset:54272
	ds_read_b128 v[212:215], v182 offset:55296
	ds_read_b128 v[216:219], v182 offset:56320
	global_load_lds_dwordx4 v158, s[24:25]
	s_add_i32 m0, s50, 0x2000
	s_add_u32 s22, s22, 0xc000
	v_lshl_add_u64 v[220:221], s[24:25], 0, v[162:163]
	s_addc_u32 s23, s23, 0
	s_add_i32 s24, s51, s30
	global_load_lds_dwordx4 v[220:221], off
	s_mov_b32 m0, s24
	s_nop 0
	global_load_lds_dwordx4 v158, s[22:23]
	s_add_i32 m0, s24, 0x2000
	s_nop 0
	global_load_lds_dwordx4 v162, s[22:23]
	s_waitcnt vmcnt(6)
	s_waitcnt lgkmcnt(0)
	s_barrier
	s_setprio 1
	s_waitcnt lgkmcnt(0)
	v_mfma_i32_16x16x64_i8 v[62:65], v[66:69], v[188:191], v[62:65]
	v_mfma_i32_16x16x64_i8 v[58:61], v[74:77], v[188:191], v[58:61]
	v_mfma_i32_16x16x64_i8 v[46:49], v[66:69], v[196:199], v[46:49]
	v_mfma_i32_16x16x64_i8 v[42:45], v[74:77], v[196:199], v[42:45]
	v_mfma_i32_16x16x64_i8 v[30:33], v[66:69], v[204:207], v[30:33]
	v_mfma_i32_16x16x64_i8 v[26:29], v[74:77], v[204:207], v[26:29]
	v_mfma_i32_16x16x64_i8 v[14:17], v[66:69], v[212:215], v[14:17]
	v_mfma_i32_16x16x64_i8 v[10:13], v[74:77], v[212:215], v[10:13]
	v_mfma_i32_16x16x64_i8 v[62:65], v[70:73], v[192:195], v[62:65]
	v_mfma_i32_16x16x64_i8 v[58:61], v[78:81], v[192:195], v[58:61]
	v_mfma_i32_16x16x64_i8 v[46:49], v[70:73], v[200:203], v[46:49]
	v_mfma_i32_16x16x64_i8 v[42:45], v[78:81], v[200:203], v[42:45]
	v_mfma_i32_16x16x64_i8 v[30:33], v[70:73], v[208:211], v[30:33]
	v_mfma_i32_16x16x64_i8 v[26:29], v[78:81], v[208:211], v[26:29]
	v_mfma_i32_16x16x64_i8 v[14:17], v[70:73], v[216:219], v[14:17]
	v_mfma_i32_16x16x64_i8 v[10:13], v[78:81], v[216:219], v[10:13]
	v_mfma_i32_16x16x64_i8 v[54:57], v[146:149], v[188:191], v[54:57]
	v_mfma_i32_16x16x64_i8 v[50:53], v[174:177], v[188:191], v[50:53]
	v_mfma_i32_16x16x64_i8 v[38:41], v[146:149], v[196:199], v[38:41]
	v_mfma_i32_16x16x64_i8 v[34:37], v[174:177], v[196:199], v[34:37]
	v_mfma_i32_16x16x64_i8 v[22:25], v[146:149], v[204:207], v[22:25]
	v_mfma_i32_16x16x64_i8 v[18:21], v[174:177], v[204:207], v[18:21]
	v_mfma_i32_16x16x64_i8 v[6:9], v[146:149], v[212:215], v[6:9]
	v_mfma_i32_16x16x64_i8 v[2:5], v[174:177], v[212:215], v[2:5]
	v_mfma_i32_16x16x64_i8 v[54:57], v[150:153], v[192:195], v[54:57]
	v_mfma_i32_16x16x64_i8 v[50:53], v[184:187], v[192:195], v[50:53]
	v_mfma_i32_16x16x64_i8 v[38:41], v[150:153], v[200:203], v[38:41]
	v_mfma_i32_16x16x64_i8 v[34:37], v[184:187], v[200:203], v[34:37]
	v_mfma_i32_16x16x64_i8 v[22:25], v[150:153], v[208:211], v[22:25]
	v_mfma_i32_16x16x64_i8 v[18:21], v[184:187], v[208:211], v[18:21]
	v_mfma_i32_16x16x64_i8 v[6:9], v[150:153], v[216:219], v[6:9]
	v_mfma_i32_16x16x64_i8 v[2:5], v[184:187], v[216:219], v[2:5]
	s_setprio 0
	s_barrier
	s_add_i32 s49, s49, 2
	s_add_u32 s18, s18, 0x10000
	s_addc_u32 s19, s19, 0
	s_add_u32 s47, s47, 0x10000
	s_addc_u32 s48, s48, 0
	s_cmpk_gt_u32 s49, 0x53
	s_cbranch_scc0 .LBB0_1393
	s_and_b64 vcc, exec, s[14:15]
	s_cbranch_vccz .LBB0_1396
	s_barrier

; #define PG8_STAGE(bufoff, gbase, voff) do { _Pragma("unroll") for (int _i = 0; _i < 2; ++_i) \
;         __builtin_amdgcn_global_load_lds((const unsigned*)((const char*)(gbase) + (voff)[_i]), (LAS unsigned*)(lds + (bufoff) + ldsw + _i * 8192), 16, 0, 0); } while (0)
; #define PG8_LDA(dst, b, h) do { _Pragma("unroll") for (int m = 0; m < 4; ++m) _Pragma("unroll") for (int k = 0; k < 2; ++k) dst[m][k] = *(const LAS bf16x8*)(lds + PG8_SA(b, h) + aoff + m * 2048 + k * 1024); } while (0)
; #define PG8_LDB(dst, b, h) do { _Pragma("unroll") for (int n = 0; n < 2; ++n) _Pragma("unroll") for (int k = 0; k < 2; ++k) dst[n][k] = *(const LAS bf16x8*)(lds + PG8_SB(b, h) + boff + n * 2048 + k * 1024); } while (0)
; #define PG8_WAIT_V(n) asm volatile("s_waitcnt vmcnt(" #n ")" ::: "memory")
; #define PG8_WAIT_L(n) asm volatile("s_waitcnt lgkmcnt(" #n ")" ::: "memory")
; #define PG8_BAR __builtin_amdgcn_s_barrier()
; #define PG8_SCHED __builtin_amdgcn_sched_barrier(0)
; template <class Epi, class Sched, bool I8 = false>
; __device__ __forceinline__ void gemm_phase(LAS unsigned char* lds, const Gemm g, const Sched& S, const Epi& E) {
;     ...
;         for (int t = 0; t < nt; t += 2) {
;             const bool last = (t == nt - 2);
;             const char* a1 = cA + (size_t)(t + 1) * kstep;
;             const char* a2 = last ? nA : cA + (size_t)(t + 2) * kstep; const char* b2 = last ? nB : cB + (size_t)(t + 2) * kstep;
;             const char* a3 = a2 + kstep; const char* b3 = b2 + kstep;
;             PG8_LDB(B0, 0, 0); PG8_LDB(B1, 0, 1); PG8_SCHED; PG8_LDA(At, 0, 0); PG8_STAGE(PG8_SA(1, 1), a1 + hstepA, voffA);
;             PG8_WAIT_V(8); PG8_WAIT_L(0); PG8_BAR; PG8_MMA(0, 0, At, B0); PG8_MMA(0, 1, At, B1); PG8_BAR; PG8_SCHED;
;             PG8_LDA(At, 0, 1); PG8_STAGE(PG8_SB(0, 0), b2, voffB); PG8_STAGE(PG8_SB(0, 1), b2 + hstepB, voffB); PG8_STAGE(PG8_SA(0, 0), a2, voffA);
;             PG8_WAIT_V(8); PG8_WAIT_L(0); PG8_BAR; PG8_MMA(1, 0, At, B0); PG8_MMA(1, 1, At, B1); PG8_BAR; PG8_SCHED;
.LBB0_1482:
	ds_read_b128 v[152:155], v182
	ds_read_b128 v[156:159], v182 offset:1024
	ds_read_b128 v[160:163], v182 offset:2048
	ds_read_b128 v[164:167], v182 offset:3072
	ds_read_b128 v[168:171], v183
	ds_read_b128 v[172:175], v183 offset:1024
	ds_read_b128 v[176:179], v183 offset:2048
	ds_read_b128 v[186:189], v183 offset:3072
	s_add_u32 s38, s8, 0x4000
	s_addc_u32 s39, s9, 0
	s_cmp_eq_u32 s47, 60
	s_cselect_b32 s42, s31, s38
	s_cselect_b32 s43, s7, s39
	s_cselect_b32 s40, s44, s45
	s_cselect_b32 s41, s29, s46
	s_add_u32 s38, s42, 0x8000
	s_addc_u32 s39, s43, 0
	s_sub_u32 s98, s8, 0x4000
	s_subb_u32 s99, s9, 0
	s_mov_b32 m0, s58
	s_nop 0
	global_load_lds_dwordx4 v130, s[98:99]
	s_mov_b32 m0, s59
	s_nop 0
	global_load_lds_dwordx4 v134, s[98:99]
	s_add_i32 m0, s33, 0xc000
	ds_read_b128 v[190:193], v184
	ds_read_b128 v[194:197], v184 offset:1024
	ds_read_b128 v[198:201], v184 offset:2048
	ds_read_b128 v[202:205], v184 offset:3072
	ds_read_b128 v[206:209], v184 offset:4096
	ds_read_b128 v[210:213], v184 offset:5120
	ds_read_b128 v[214:217], v184 offset:6144
	ds_read_b128 v[218:221], v184 offset:7168
	global_load_lds_dwordx4 v144, s[8:9]
	s_add_i32 m0, s33, 0xe000
	s_nop 0
	global_load_lds_dwordx4 v146, s[8:9]
	s_waitcnt vmcnt(8)
	s_waitcnt lgkmcnt(0)
	s_barrier
	s_setprio 1
	s_waitcnt lgkmcnt(0)
	v_mfma_f32_16x16x32_bf16 v[126:129], v[152:155], v[190:193], v[126:129]
	v_mfma_f32_16x16x32_bf16 v[122:125], v[160:163], v[190:193], v[122:125]
	v_mfma_f32_16x16x32_bf16 v[110:113], v[152:155], v[198:201], v[110:113]
	v_mfma_f32_16x16x32_bf16 v[106:109], v[160:163], v[198:201], v[106:109]
	v_mfma_f32_16x16x32_bf16 v[94:97], v[152:155], v[206:209], v[94:97]
	v_mfma_f32_16x16x32_bf16 v[90:93], v[160:163], v[206:209], v[90:93]
	v_mfma_f32_16x16x32_bf16 v[78:81], v[152:155], v[214:217], v[78:81]
	v_mfma_f32_16x16x32_bf16 v[74:77], v[160:163], v[214:217], v[74:77]
	v_mfma_f32_16x16x32_bf16 v[126:129], v[156:159], v[194:197], v[126:129]
	v_mfma_f32_16x16x32_bf16 v[122:125], v[164:167], v[194:197], v[122:125]
	v_mfma_f32_16x16x32_bf16 v[110:113], v[156:159], v[202:205], v[110:113]
	v_mfma_f32_16x16x32_bf16 v[106:109], v[164:167], v[202:205], v[106:109]
	v_mfma_f32_16x16x32_bf16 v[94:97], v[156:159], v[210:213], v[94:97]
	v_mfma_f32_16x16x32_bf16 v[90:93], v[164:167], v[210:213], v[90:93]
	v_mfma_f32_16x16x32_bf16 v[78:81], v[156:159], v[218:221], v[78:81]
	v_mfma_f32_16x16x32_bf16 v[74:77], v[164:167], v[218:221], v[74:77]
	v_mfma_f32_16x16x32_bf16 v[118:121], v[168:171], v[190:193], v[118:121]
	v_mfma_f32_16x16x32_bf16 v[114:117], v[176:179], v[190:193], v[114:117]
	v_mfma_f32_16x16x32_bf16 v[102:105], v[168:171], v[198:201], v[102:105]
	v_mfma_f32_16x16x32_bf16 v[98:101], v[176:179], v[198:201], v[98:101]
	v_mfma_f32_16x16x32_bf16 v[86:89], v[168:171], v[206:209], v[86:89]
	v_mfma_f32_16x16x32_bf16 v[82:85], v[176:179], v[206:209], v[82:85]
	v_mfma_f32_16x16x32_bf16 v[70:73], v[168:171], v[214:217], v[70:73]
	v_mfma_f32_16x16x32_bf16 v[66:69], v[176:179], v[214:217], v[66:69]
	v_mfma_f32_16x16x32_bf16 v[118:121], v[172:175], v[194:197], v[118:121]
	v_mfma_f32_16x16x32_bf16 v[114:117], v[186:189], v[194:197], v[114:117]
	v_mfma_f32_16x16x32_bf16 v[102:105], v[172:175], v[202:205], v[102:105]
	v_mfma_f32_16x16x32_bf16 v[98:101], v[186:189], v[202:205], v[98:101]
	v_mfma_f32_16x16x32_bf16 v[86:89], v[172:175], v[210:213], v[86:89]
	v_mfma_f32_16x16x32_bf16 v[82:85], v[186:189], v[210:213], v[82:85]
	v_mfma_f32_16x16x32_bf16 v[70:73], v[172:175], v[218:221], v[70:73]
	v_mfma_f32_16x16x32_bf16 v[66:69], v[186:189], v[218:221], v[66:69]
	s_setprio 0
	s_barrier
	s_add_i32 s48, s63, s25
	s_mov_b32 m0, s48
	ds_read_b128 v[190:193], v184 offset:16384
	ds_read_b128 v[194:197], v184 offset:17408
	ds_read_b128 v[198:201], v184 offset:18432
	ds_read_b128 v[202:205], v184 offset:19456
	ds_read_b128 v[206:209], v184 offset:20480
	ds_read_b128 v[210:213], v184 offset:21504
	ds_read_b128 v[214:217], v184 offset:22528
	ds_read_b128 v[218:221], v184 offset:23552
	global_load_lds_dwordx4 v132, s[40:41]
	s_add_i32 m0, s48, 0x2000
	s_add_u32 s48, s40, 0x4000
	s_addc_u32 s49, s41, 0
	s_add_i32 s50, s64, s25
	global_load_lds_dwordx4 v136, s[40:41]
	s_mov_b32 m0, s50
	s_nop 0
	global_load_lds_dwordx4 v132, s[48:49]
	s_add_i32 m0, s50, 0x2000
	s_nop 0
	global_load_lds_dwordx4 v136, s[48:49]
	s_waitcnt vmcnt(6)
	s_waitcnt lgkmcnt(0)
	s_barrier
	s_setprio 1
	s_waitcnt lgkmcnt(0)
	v_mfma_f32_16x16x32_bf16 v[62:65], v[152:155], v[190:193], v[62:65]
	v_mfma_f32_16x16x32_bf16 v[58:61], v[160:163], v[190:193], v[58:61]
	v_mfma_f32_16x16x32_bf16 v[46:49], v[152:155], v[198:201], v[46:49]
	v_mfma_f32_16x16x32_bf16 v[42:45], v[160:163], v[198:201], v[42:45]
	v_mfma_f32_16x16x32_bf16 v[30:33], v[152:155], v[206:209], v[30:33]
	v_mfma_f32_16x16x32_bf16 v[26:29], v[160:163], v[206:209], v[26:29]
	v_mfma_f32_16x16x32_bf16 v[14:17], v[152:155], v[214:217], v[14:17]
	v_mfma_f32_16x16x32_bf16 v[10:13], v[160:163], v[214:217], v[10:13]
	v_mfma_f32_16x16x32_bf16 v[62:65], v[156:159], v[194:197], v[62:65]
	v_mfma_f32_16x16x32_bf16 v[58:61], v[164:167], v[194:197], v[58:61]
	v_mfma_f32_16x16x32_bf16 v[46:49], v[156:159], v[202:205], v[46:49]
	v_mfma_f32_16x16x32_bf16 v[42:45], v[164:167], v[202:205], v[42:45]
	v_mfma_f32_16x16x32_bf16 v[30:33], v[156:159], v[210:213], v[30:33]
	v_mfma_f32_16x16x32_bf16 v[26:29], v[164:167], v[210:213], v[26:29]
	v_mfma_f32_16x16x32_bf16 v[14:17], v[156:159], v[218:221], v[14:17]
	v_mfma_f32_16x16x32_bf16 v[10:13], v[164:167], v[218:221], v[10:13]
	v_mfma_f32_16x16x32_bf16 v[54:57], v[168:171], v[190:193], v[54:57]
	v_mfma_f32_16x16x32_bf16 v[50:53], v[176:179], v[190:193], v[50:53]
	v_mfma_f32_16x16x32_bf16 v[38:41], v[168:171], v[198:201], v[38:41]
	v_mfma_f32_16x16x32_bf16 v[34:37], v[176:179], v[198:201], v[34:37]
	v_mfma_f32_16x16x32_bf16 v[22:25], v[168:171], v[206:209], v[22:25]
	v_mfma_f32_16x16x32_bf16 v[18:21], v[176:179], v[206:209], v[18:21]
	v_mfma_f32_16x16x32_bf16 v[6:9], v[168:171], v[214:217], v[6:9]
	v_mfma_f32_16x16x32_bf16 v[2:5], v[176:179], v[214:217], v[2:5]
	v_mfma_f32_16x16x32_bf16 v[54:57], v[172:175], v[194:197], v[54:57]
	v_mfma_f32_16x16x32_bf16 v[50:53], v[186:189], v[194:197], v[50:53]
	v_mfma_f32_16x16x32_bf16 v[38:41], v[172:175], v[202:205], v[38:41]
	v_mfma_f32_16x16x32_bf16 v[34:37], v[186:189], v[202:205], v[34:37]
	v_mfma_f32_16x16x32_bf16 v[22:25], v[172:175], v[210:213], v[22:25]
	v_mfma_f32_16x16x32_bf16 v[18:21], v[186:189], v[210:213], v[18:21]
	v_mfma_f32_16x16x32_bf16 v[6:9], v[172:175], v[218:221], v[6:9]
	v_mfma_f32_16x16x32_bf16 v[2:5], v[186:189], v[218:221], v[2:5]
	s_setprio 0
	s_barrier
; #define PG8_STAGE(bufoff, gbase, voff) do { _Pragma("unroll") for (int _i = 0; _i < 2; ++_i) \
;         __builtin_amdgcn_global_load_lds((const unsigned*)((const char*)(gbase) + (voff)[_i]), (LAS unsigned*)(lds + (bufoff) + ldsw + _i * 8192), 16, 0, 0); } while (0)
; #define PG8_LDA(dst, b, h) do { _Pragma("unroll") for (int m = 0; m < 4; ++m) _Pragma("unroll") for (int k = 0; k < 2; ++k) dst[m][k] = *(const LAS bf16x8*)(lds + PG8_SA(b, h) + aoff + m * 2048 + k * 1024); } while (0)
; #define PG8_LDB(dst, b, h) do { _Pragma("unroll") for (int n = 0; n < 2; ++n) _Pragma("unroll") for (int k = 0; k < 2; ++k) dst[n][k] = *(const LAS bf16x8*)(lds + PG8_SB(b, h) + boff + n * 2048 + k * 1024); } while (0)
; #define PG8_WAIT_V(n) asm volatile("s_waitcnt vmcnt(" #n ")" ::: "memory")
; #define PG8_WAIT_L(n) asm volatile("s_waitcnt lgkmcnt(" #n ")" ::: "memory")
; #define PG8_BAR __builtin_amdgcn_s_barrier()
; #define PG8_SCHED __builtin_amdgcn_sched_barrier(0)
; template <class Epi, class Sched, bool I8 = false>
; __device__ __forceinline__ void gemm_phase(LAS unsigned char* lds, const Gemm g, const Sched& S, const Epi& E) {
;     ...
;         for (int t = 0; t < nt; t += 2) {
;             const bool last = (t == nt - 2);
;     ...
;             PG8_LDB(B0, 1, 0); PG8_LDB(B1, 1, 1); PG8_SCHED; PG8_LDA(At, 1, 0); PG8_STAGE(PG8_SA(0, 1), a2 + hstepA, voffA);
;             PG8_WAIT_V(8); PG8_WAIT_L(0); PG8_BAR; PG8_MMA(0, 0, At, B0); PG8_MMA(0, 1, At, B1); PG8_BAR; PG8_SCHED;
;             PG8_LDA(At, 1, 1); PG8_STAGE(PG8_SB(1, 0), b3, voffB); PG8_STAGE(PG8_SB(1, 1), b3 + hstepB, voffB); PG8_STAGE(PG8_SA(1, 0), a3, voffA);
;             PG8_WAIT_V(8); PG8_WAIT_L(0); PG8_BAR; PG8_MMA(1, 0, At, B0); PG8_MMA(1, 1, At, B1); PG8_BAR; PG8_SCHED;
	s_add_i32 s48, 0, 0x18000
	v_add_u32_e32 v138, s48, v181
	s_add_i32 s49, 0, 0x1c000
	ds_read_b128 v[152:155], v138
	ds_read_b128 v[156:159], v138 offset:1024
	ds_read_b128 v[160:163], v138 offset:2048
	ds_read_b128 v[164:167], v138 offset:3072
	v_add_u32_e32 v138, s49, v181
	ds_read_b128 v[168:171], v138
	ds_read_b128 v[172:175], v138 offset:1024
	ds_read_b128 v[176:179], v138 offset:2048
	ds_read_b128 v[186:189], v138 offset:3072
	s_mov_b32 m0, s33
	s_nop 0
	global_load_lds_dwordx4 v130, s[42:43]
	s_mov_b32 m0, s52
	s_nop 0
	global_load_lds_dwordx4 v134, s[42:43]
	s_add_u32 s42, s42, 0x4000
	s_addc_u32 s43, s43, 0
	s_mov_b32 m0, s53
	ds_read_b128 v[190:193], v184 offset:32768
	ds_read_b128 v[194:197], v184 offset:33792
	ds_read_b128 v[198:201], v184 offset:34816
	ds_read_b128 v[202:205], v184 offset:35840
	ds_read_b128 v[206:209], v184 offset:36864
	ds_read_b128 v[210:213], v184 offset:37888
	ds_read_b128 v[214:217], v184 offset:38912
	ds_read_b128 v[218:221], v184 offset:39936
	global_load_lds_dwordx4 v130, s[42:43]
	s_mov_b32 m0, s54
	s_nop 0
	global_load_lds_dwordx4 v134, s[42:43]
	s_waitcnt vmcnt(8)
	s_waitcnt lgkmcnt(0)
	s_barrier
	s_setprio 1
	s_waitcnt lgkmcnt(0)
	v_mfma_f32_16x16x32_bf16 v[126:129], v[152:155], v[190:193], v[126:129]
	v_mfma_f32_16x16x32_bf16 v[122:125], v[160:163], v[190:193], v[122:125]
	v_mfma_f32_16x16x32_bf16 v[110:113], v[152:155], v[198:201], v[110:113]
	v_mfma_f32_16x16x32_bf16 v[106:109], v[160:163], v[198:201], v[106:109]
	v_mfma_f32_16x16x32_bf16 v[94:97], v[152:155], v[206:209], v[94:97]
	v_mfma_f32_16x16x32_bf16 v[90:93], v[160:163], v[206:209], v[90:93]
	v_mfma_f32_16x16x32_bf16 v[78:81], v[152:155], v[214:217], v[78:81]
	v_mfma_f32_16x16x32_bf16 v[74:77], v[160:163], v[214:217], v[74:77]
	v_mfma_f32_16x16x32_bf16 v[126:129], v[156:159], v[194:197], v[126:129]
	v_mfma_f32_16x16x32_bf16 v[122:125], v[164:167], v[194:197], v[122:125]
	v_mfma_f32_16x16x32_bf16 v[110:113], v[156:159], v[202:205], v[110:113]
	v_mfma_f32_16x16x32_bf16 v[106:109], v[164:167], v[202:205], v[106:109]
	v_mfma_f32_16x16x32_bf16 v[94:97], v[156:159], v[210:213], v[94:97]
	v_mfma_f32_16x16x32_bf16 v[90:93], v[164:167], v[210:213], v[90:93]
	v_mfma_f32_16x16x32_bf16 v[78:81], v[156:159], v[218:221], v[78:81]
	v_mfma_f32_16x16x32_bf16 v[74:77], v[164:167], v[218:221], v[74:77]
	v_mfma_f32_16x16x32_bf16 v[118:121], v[168:171], v[190:193], v[118:121]
	v_mfma_f32_16x16x32_bf16 v[114:117], v[176:179], v[190:193], v[114:117]
	v_mfma_f32_16x16x32_bf16 v[102:105], v[168:171], v[198:201], v[102:105]
	v_mfma_f32_16x16x32_bf16 v[98:101], v[176:179], v[198:201], v[98:101]
	v_mfma_f32_16x16x32_bf16 v[86:89], v[168:171], v[206:209], v[86:89]
	v_mfma_f32_16x16x32_bf16 v[82:85], v[176:179], v[206:209], v[82:85]
	v_mfma_f32_16x16x32_bf16 v[70:73], v[168:171], v[214:217], v[70:73]
	v_mfma_f32_16x16x32_bf16 v[66:69], v[176:179], v[214:217], v[66:69]
	v_mfma_f32_16x16x32_bf16 v[118:121], v[172:175], v[194:197], v[118:121]
	v_mfma_f32_16x16x32_bf16 v[114:117], v[186:189], v[194:197], v[114:117]
	v_mfma_f32_16x16x32_bf16 v[102:105], v[172:175], v[202:205], v[102:105]
	v_mfma_f32_16x16x32_bf16 v[98:101], v[186:189], v[202:205], v[98:101]
	v_mfma_f32_16x16x32_bf16 v[86:89], v[172:175], v[210:213], v[86:89]
	v_mfma_f32_16x16x32_bf16 v[82:85], v[186:189], v[210:213], v[82:85]
	v_mfma_f32_16x16x32_bf16 v[70:73], v[172:175], v[218:221], v[70:73]
	v_mfma_f32_16x16x32_bf16 v[66:69], v[186:189], v[218:221], v[66:69]
	s_setprio 0
	s_barrier
	s_add_u32 s42, s40, 0x8000
	s_addc_u32 s43, s41, 0
	s_add_i32 s48, s48, s25
	s_mov_b32 m0, s48
	ds_read_b128 v[190:193], v184 offset:49152
	ds_read_b128 v[194:197], v184 offset:50176
	ds_read_b128 v[198:201], v184 offset:51200
	ds_read_b128 v[202:205], v184 offset:52224
	ds_read_b128 v[206:209], v184 offset:53248
	ds_read_b128 v[210:213], v184 offset:54272
	ds_read_b128 v[214:217], v184 offset:55296
	ds_read_b128 v[218:221], v184 offset:56320
	global_load_lds_dwordx4 v132, s[42:43]
	s_add_i32 m0, s48, 0x2000
	s_add_u32 s40, s40, 0xc000
	v_lshl_add_u64 v[222:223], s[42:43], 0, v[136:137]
	s_addc_u32 s41, s41, 0
	s_add_i32 s42, s49, s25
	global_load_lds_dwordx4 v[222:223], off
	s_mov_b32 m0, s42
	s_nop 0
	global_load_lds_dwordx4 v132, s[40:41]
	s_add_i32 m0, s42, 0x2000
	s_nop 0
	global_load_lds_dwordx4 v136, s[40:41]
	s_waitcnt vmcnt(6)
	s_waitcnt lgkmcnt(0)
	s_barrier
	s_setprio 1
	s_waitcnt lgkmcnt(0)
	v_mfma_f32_16x16x32_bf16 v[62:65], v[152:155], v[190:193], v[62:65]
	v_mfma_f32_16x16x32_bf16 v[58:61], v[160:163], v[190:193], v[58:61]
	v_mfma_f32_16x16x32_bf16 v[46:49], v[152:155], v[198:201], v[46:49]
	v_mfma_f32_16x16x32_bf16 v[42:45], v[160:163], v[198:201], v[42:45]
	v_mfma_f32_16x16x32_bf16 v[30:33], v[152:155], v[206:209], v[30:33]
	v_mfma_f32_16x16x32_bf16 v[26:29], v[160:163], v[206:209], v[26:29]
	v_mfma_f32_16x16x32_bf16 v[14:17], v[152:155], v[214:217], v[14:17]
	v_mfma_f32_16x16x32_bf16 v[10:13], v[160:163], v[214:217], v[10:13]
	v_mfma_f32_16x16x32_bf16 v[62:65], v[156:159], v[194:197], v[62:65]
	v_mfma_f32_16x16x32_bf16 v[58:61], v[164:167], v[194:197], v[58:61]
	v_mfma_f32_16x16x32_bf16 v[46:49], v[156:159], v[202:205], v[46:49]
	v_mfma_f32_16x16x32_bf16 v[42:45], v[164:167], v[202:205], v[42:45]
	v_mfma_f32_16x16x32_bf16 v[30:33], v[156:159], v[210:213], v[30:33]
	v_mfma_f32_16x16x32_bf16 v[26:29], v[164:167], v[210:213], v[26:29]
	v_mfma_f32_16x16x32_bf16 v[14:17], v[156:159], v[218:221], v[14:17]
	v_mfma_f32_16x16x32_bf16 v[10:13], v[164:167], v[218:221], v[10:13]
	v_mfma_f32_16x16x32_bf16 v[54:57], v[168:171], v[190:193], v[54:57]
	v_mfma_f32_16x16x32_bf16 v[50:53], v[176:179], v[190:193], v[50:53]
	v_mfma_f32_16x16x32_bf16 v[38:41], v[168:171], v[198:201], v[38:41]
	v_mfma_f32_16x16x32_bf16 v[34:37], v[176:179], v[198:201], v[34:37]
	v_mfma_f32_16x16x32_bf16 v[22:25], v[168:171], v[206:209], v[22:25]
	v_mfma_f32_16x16x32_bf16 v[18:21], v[176:179], v[206:209], v[18:21]
	v_mfma_f32_16x16x32_bf16 v[6:9], v[168:171], v[214:217], v[6:9]
	v_mfma_f32_16x16x32_bf16 v[2:5], v[176:179], v[214:217], v[2:5]
	v_mfma_f32_16x16x32_bf16 v[54:57], v[172:175], v[194:197], v[54:57]
	v_mfma_f32_16x16x32_bf16 v[50:53], v[186:189], v[194:197], v[50:53]
	v_mfma_f32_16x16x32_bf16 v[38:41], v[172:175], v[202:205], v[38:41]
	v_mfma_f32_16x16x32_bf16 v[34:37], v[186:189], v[202:205], v[34:37]
	v_mfma_f32_16x16x32_bf16 v[22:25], v[172:175], v[210:213], v[22:25]
	v_mfma_f32_16x16x32_bf16 v[18:21], v[186:189], v[210:213], v[18:21]
	v_mfma_f32_16x16x32_bf16 v[6:9], v[172:175], v[218:221], v[6:9]
	v_mfma_f32_16x16x32_bf16 v[2:5], v[186:189], v[218:221], v[2:5]
	s_setprio 0
	s_barrier
	s_add_i32 s47, s47, 2
	s_add_u32 s8, s8, 0x10000
	s_addc_u32 s9, s9, 0
	s_add_u32 s45, s45, 0x10000
	s_addc_u32 s46, s46, 0
	s_cmp_gt_u32 s47, 61
	s_cbranch_scc0 .LBB0_1482
	s_and_b64 vcc, exec, s[20:21]
	s_cbranch_vccz .LBB0_1485
	s_barrier

; #define PG8_STAGE(bufoff, gbase, voff) do { _Pragma("unroll") for (int _i = 0; _i < 2; ++_i) \
;         __builtin_amdgcn_global_load_lds((const unsigned*)((const char*)(gbase) + (voff)[_i]), (LAS unsigned*)(lds + (bufoff) + ldsw + _i * 8192), 16, 0, 0); } while (0)
; #define PG8_LDA(dst, b, h) do { _Pragma("unroll") for (int m = 0; m < 4; ++m) _Pragma("unroll") for (int k = 0; k < 2; ++k) dst[m][k] = *(const LAS bf16x8*)(lds + PG8_SA(b, h) + aoff + m * 2048 + k * 1024); } while (0)
; #define PG8_LDB(dst, b, h) do { _Pragma("unroll") for (int n = 0; n < 2; ++n) _Pragma("unroll") for (int k = 0; k < 2; ++k) dst[n][k] = *(const LAS bf16x8*)(lds + PG8_SB(b, h) + boff + n * 2048 + k * 1024); } while (0)
; #define PG8_WAIT_V(n) asm volatile("s_waitcnt vmcnt(" #n ")" ::: "memory")
; #define PG8_WAIT_L(n) asm volatile("s_waitcnt lgkmcnt(" #n ")" ::: "memory")
; #define PG8_BAR __builtin_amdgcn_s_barrier()
; #define PG8_SCHED __builtin_amdgcn_sched_barrier(0)
; template <class Epi, class Sched, bool I8 = false>
; __device__ __forceinline__ void gemm_phase(LAS unsigned char* lds, const Gemm g, const Sched& S, const Epi& E) {
;     ...
;             PG8_LDB(B0, 0, 0); PG8_LDB(B1, 0, 1); PG8_SCHED; PG8_LDA(At, 0, 0); PG8_STAGE(PG8_SA(1, 1), a1 + hstepA, voffA);
;             PG8_WAIT_V(8); PG8_WAIT_L(0); PG8_BAR; PG8_MMA(0, 0, At, B0); PG8_MMA(0, 1, At, B1); PG8_BAR; PG8_SCHED;
;             PG8_LDA(At, 0, 1); PG8_STAGE(PG8_SB(0, 0), b2, voffB); PG8_STAGE(PG8_SB(0, 1), b2 + hstepB, voffB); PG8_STAGE(PG8_SA(0, 0), a2, voffA);
;             PG8_WAIT_V(8); PG8_WAIT_L(0); PG8_BAR; PG8_MMA(1, 0, At, B0); PG8_MMA(1, 1, At, B1); PG8_BAR; PG8_SCHED;
.LBB0_2685:
	ds_read_b128 v[130:133], v166
	ds_read_b128 v[134:137], v166 offset:1024
	ds_read_b128 v[158:161], v166 offset:2048
	ds_read_b128 v[170:173], v166 offset:3072
	ds_read_b128 v[174:177], v167
	ds_read_b128 v[178:181], v167 offset:1024
	ds_read_b128 v[182:185], v167 offset:2048
	ds_read_b128 v[186:189], v167 offset:3072
	s_add_u32 s12, s10, 0x4000
	s_addc_u32 s13, s11, 0
	s_cmp_eq_u32 s45, 4
	s_cselect_b32 s16, s40, s12
	s_cselect_b32 s17, s39, s13
	s_cselect_b32 s14, s42, s43
	s_cselect_b32 s15, s41, s44
	s_add_u32 s12, s16, 0x8000
	s_addc_u32 s13, s17, 0
	s_sub_u32 s98, s10, 0x4000
	s_subb_u32 s99, s11, 0
	s_mov_b32 m0, s33
	s_nop 0
	global_load_lds_dwordx4 v144, s[98:99]
	s_mov_b32 m0, s34
	s_nop 0
	global_load_lds_dwordx4 v140, s[98:99]
	s_add_i32 m0, s26, 0xc000
	ds_read_b128 v[190:193], v168
	ds_read_b128 v[194:197], v168 offset:1024
	ds_read_b128 v[198:201], v168 offset:2048
	ds_read_b128 v[202:205], v168 offset:3072
	ds_read_b128 v[206:209], v168 offset:4096
	ds_read_b128 v[210:213], v168 offset:5120
	ds_read_b128 v[214:217], v168 offset:6144
	ds_read_b128 v[218:221], v168 offset:7168
	global_load_lds_dwordx4 v150, s[10:11]
	s_add_i32 m0, s26, 0xe000
	s_nop 0
	global_load_lds_dwordx4 v152, s[10:11]
	s_waitcnt vmcnt(8)
	s_waitcnt lgkmcnt(0)
	s_barrier
	s_setprio 1
	s_waitcnt lgkmcnt(0)
	v_mfma_f32_16x16x32_bf16 v[126:129], v[130:133], v[190:193], v[126:129]
	v_mfma_f32_16x16x32_bf16 v[122:125], v[158:161], v[190:193], v[122:125]
	v_mfma_f32_16x16x32_bf16 v[118:121], v[130:133], v[198:201], v[118:121]
	v_mfma_f32_16x16x32_bf16 v[114:117], v[158:161], v[198:201], v[114:117]
	v_mfma_f32_16x16x32_bf16 v[110:113], v[130:133], v[206:209], v[110:113]
	v_mfma_f32_16x16x32_bf16 v[106:109], v[158:161], v[206:209], v[106:109]
	v_mfma_f32_16x16x32_bf16 v[102:105], v[130:133], v[214:217], v[102:105]
	v_mfma_f32_16x16x32_bf16 v[98:101], v[158:161], v[214:217], v[98:101]
	v_mfma_f32_16x16x32_bf16 v[126:129], v[134:137], v[194:197], v[126:129]
	v_mfma_f32_16x16x32_bf16 v[122:125], v[170:173], v[194:197], v[122:125]
	v_mfma_f32_16x16x32_bf16 v[118:121], v[134:137], v[202:205], v[118:121]
	v_mfma_f32_16x16x32_bf16 v[114:117], v[170:173], v[202:205], v[114:117]
	v_mfma_f32_16x16x32_bf16 v[110:113], v[134:137], v[210:213], v[110:113]
	v_mfma_f32_16x16x32_bf16 v[106:109], v[170:173], v[210:213], v[106:109]
	v_mfma_f32_16x16x32_bf16 v[102:105], v[134:137], v[218:221], v[102:105]
	v_mfma_f32_16x16x32_bf16 v[98:101], v[170:173], v[218:221], v[98:101]
	v_mfma_f32_16x16x32_bf16 v[62:65], v[174:177], v[190:193], v[62:65]
	v_mfma_f32_16x16x32_bf16 v[58:61], v[182:185], v[190:193], v[58:61]
	v_mfma_f32_16x16x32_bf16 v[54:57], v[174:177], v[198:201], v[54:57]
	v_mfma_f32_16x16x32_bf16 v[50:53], v[182:185], v[198:201], v[50:53]
	v_mfma_f32_16x16x32_bf16 v[46:49], v[174:177], v[206:209], v[46:49]
	v_mfma_f32_16x16x32_bf16 v[42:45], v[182:185], v[206:209], v[42:45]
	v_mfma_f32_16x16x32_bf16 v[38:41], v[174:177], v[214:217], v[38:41]
	v_mfma_f32_16x16x32_bf16 v[34:37], v[182:185], v[214:217], v[34:37]
	v_mfma_f32_16x16x32_bf16 v[62:65], v[178:181], v[194:197], v[62:65]
	v_mfma_f32_16x16x32_bf16 v[58:61], v[186:189], v[194:197], v[58:61]
	v_mfma_f32_16x16x32_bf16 v[54:57], v[178:181], v[202:205], v[54:57]
	v_mfma_f32_16x16x32_bf16 v[50:53], v[186:189], v[202:205], v[50:53]
	v_mfma_f32_16x16x32_bf16 v[46:49], v[178:181], v[210:213], v[46:49]
	v_mfma_f32_16x16x32_bf16 v[42:45], v[186:189], v[210:213], v[42:45]
	v_mfma_f32_16x16x32_bf16 v[38:41], v[178:181], v[218:221], v[38:41]
	v_mfma_f32_16x16x32_bf16 v[34:37], v[186:189], v[218:221], v[34:37]
	s_setprio 0
	s_barrier
	s_add_i32 s46, s62, s22
	s_mov_b32 m0, s46
	ds_read_b128 v[190:193], v168 offset:16384
	ds_read_b128 v[194:197], v168 offset:17408
	ds_read_b128 v[198:201], v168 offset:18432
	ds_read_b128 v[202:205], v168 offset:19456
	ds_read_b128 v[206:209], v168 offset:20480
	ds_read_b128 v[210:213], v168 offset:21504
	ds_read_b128 v[214:217], v168 offset:22528
	ds_read_b128 v[218:221], v168 offset:23552
	global_load_lds_dwordx4 v142, s[14:15]
	s_add_i32 m0, s46, 0x2000
	s_add_u32 s46, s14, 0x4000
	s_addc_u32 s47, s15, 0
	s_add_i32 s48, s35, s22
	global_load_lds_dwordx4 v138, s[14:15]
	s_mov_b32 m0, s48
	s_nop 0
	global_load_lds_dwordx4 v142, s[46:47]
	s_add_i32 m0, s48, 0x2000
	s_nop 0
	global_load_lds_dwordx4 v138, s[46:47]
	s_waitcnt vmcnt(6)
	s_waitcnt lgkmcnt(0)
	s_barrier
	s_setprio 1
	s_waitcnt lgkmcnt(0)
	v_mfma_f32_16x16x32_bf16 v[94:97], v[130:133], v[190:193], v[94:97]
	v_mfma_f32_16x16x32_bf16 v[90:93], v[158:161], v[190:193], v[90:93]
	v_mfma_f32_16x16x32_bf16 v[86:89], v[130:133], v[198:201], v[86:89]
	v_mfma_f32_16x16x32_bf16 v[82:85], v[158:161], v[198:201], v[82:85]
	v_mfma_f32_16x16x32_bf16 v[78:81], v[130:133], v[206:209], v[78:81]
	v_mfma_f32_16x16x32_bf16 v[74:77], v[158:161], v[206:209], v[74:77]
	v_mfma_f32_16x16x32_bf16 v[70:73], v[130:133], v[214:217], v[70:73]
	v_mfma_f32_16x16x32_bf16 v[66:69], v[158:161], v[214:217], v[66:69]
	v_mfma_f32_16x16x32_bf16 v[94:97], v[134:137], v[194:197], v[94:97]
	v_mfma_f32_16x16x32_bf16 v[90:93], v[170:173], v[194:197], v[90:93]
	v_mfma_f32_16x16x32_bf16 v[86:89], v[134:137], v[202:205], v[86:89]
	v_mfma_f32_16x16x32_bf16 v[82:85], v[170:173], v[202:205], v[82:85]
	v_mfma_f32_16x16x32_bf16 v[78:81], v[134:137], v[210:213], v[78:81]
	v_mfma_f32_16x16x32_bf16 v[74:77], v[170:173], v[210:213], v[74:77]
	v_mfma_f32_16x16x32_bf16 v[70:73], v[134:137], v[218:221], v[70:73]
	v_mfma_f32_16x16x32_bf16 v[66:69], v[170:173], v[218:221], v[66:69]
	v_mfma_f32_16x16x32_bf16 v[30:33], v[174:177], v[190:193], v[30:33]
	v_mfma_f32_16x16x32_bf16 v[26:29], v[182:185], v[190:193], v[26:29]
	v_mfma_f32_16x16x32_bf16 v[22:25], v[174:177], v[198:201], v[22:25]
	v_mfma_f32_16x16x32_bf16 v[18:21], v[182:185], v[198:201], v[18:21]
	v_mfma_f32_16x16x32_bf16 v[14:17], v[174:177], v[206:209], v[14:17]
	v_mfma_f32_16x16x32_bf16 v[10:13], v[182:185], v[206:209], v[10:13]
	v_mfma_f32_16x16x32_bf16 v[6:9], v[174:177], v[214:217], v[6:9]
	v_mfma_f32_16x16x32_bf16 v[2:5], v[182:185], v[214:217], v[2:5]
	v_mfma_f32_16x16x32_bf16 v[30:33], v[178:181], v[194:197], v[30:33]
	v_mfma_f32_16x16x32_bf16 v[26:29], v[186:189], v[194:197], v[26:29]
	v_mfma_f32_16x16x32_bf16 v[22:25], v[178:181], v[202:205], v[22:25]
	v_mfma_f32_16x16x32_bf16 v[18:21], v[186:189], v[202:205], v[18:21]
	v_mfma_f32_16x16x32_bf16 v[14:17], v[178:181], v[210:213], v[14:17]
	v_mfma_f32_16x16x32_bf16 v[10:13], v[186:189], v[210:213], v[10:13]
	v_mfma_f32_16x16x32_bf16 v[6:9], v[178:181], v[218:221], v[6:9]
	v_mfma_f32_16x16x32_bf16 v[2:5], v[186:189], v[218:221], v[2:5]
	s_setprio 0
	s_barrier
; #define PG8_STAGE(bufoff, gbase, voff) do { _Pragma("unroll") for (int _i = 0; _i < 2; ++_i) \
;         __builtin_amdgcn_global_load_lds((const unsigned*)((const char*)(gbase) + (voff)[_i]), (LAS unsigned*)(lds + (bufoff) + ldsw + _i * 8192), 16, 0, 0); } while (0)
; #define PG8_LDA(dst, b, h) do { _Pragma("unroll") for (int m = 0; m < 4; ++m) _Pragma("unroll") for (int k = 0; k < 2; ++k) dst[m][k] = *(const LAS bf16x8*)(lds + PG8_SA(b, h) + aoff + m * 2048 + k * 1024); } while (0)
; #define PG8_LDB(dst, b, h) do { _Pragma("unroll") for (int n = 0; n < 2; ++n) _Pragma("unroll") for (int k = 0; k < 2; ++k) dst[n][k] = *(const LAS bf16x8*)(lds + PG8_SB(b, h) + boff + n * 2048 + k * 1024); } while (0)
; #define PG8_WAIT_V(n) asm volatile("s_waitcnt vmcnt(" #n ")" ::: "memory")
; #define PG8_WAIT_L(n) asm volatile("s_waitcnt lgkmcnt(" #n ")" ::: "memory")
; #define PG8_BAR __builtin_amdgcn_s_barrier()
; #define PG8_SCHED __builtin_amdgcn_sched_barrier(0)
; template <class Epi, class Sched, bool I8 = false>
; __device__ __forceinline__ void gemm_phase(LAS unsigned char* lds, const Gemm g, const Sched& S, const Epi& E) {
;     ...
;         for (int t = 0; t < nt; t += 2) {
;             const bool last = (t == nt - 2);
;     ...
;             PG8_LDB(B0, 1, 0); PG8_LDB(B1, 1, 1); PG8_SCHED; PG8_LDA(At, 1, 0); PG8_STAGE(PG8_SA(0, 1), a2 + hstepA, voffA);
;             PG8_WAIT_V(8); PG8_WAIT_L(0); PG8_BAR; PG8_MMA(0, 0, At, B0); PG8_MMA(0, 1, At, B1); PG8_BAR; PG8_SCHED;
;             PG8_LDA(At, 1, 1); PG8_STAGE(PG8_SB(1, 0), b3, voffB); PG8_STAGE(PG8_SB(1, 1), b3 + hstepB, voffB); PG8_STAGE(PG8_SA(1, 0), a3, voffA);
;             PG8_WAIT_V(8); PG8_WAIT_L(0); PG8_BAR; PG8_MMA(1, 0, At, B0); PG8_MMA(1, 1, At, B1); PG8_BAR; PG8_SCHED;
	s_add_i32 s46, 0, 0x18000
	v_add_u32_e32 v155, s46, v165
	s_add_i32 s47, 0, 0x1c000
	ds_read_b128 v[130:133], v155
	ds_read_b128 v[134:137], v155 offset:1024
	ds_read_b128 v[158:161], v155 offset:2048
	ds_read_b128 v[170:173], v155 offset:3072
	v_add_u32_e32 v155, s47, v165
	ds_read_b128 v[174:177], v155
	ds_read_b128 v[178:181], v155 offset:1024
	ds_read_b128 v[182:185], v155 offset:2048
	ds_read_b128 v[186:189], v155 offset:3072
	s_mov_b32 m0, s26
	s_nop 0
	global_load_lds_dwordx4 v144, s[16:17]
	s_mov_b32 m0, s27
	s_nop 0
	global_load_lds_dwordx4 v140, s[16:17]
	s_add_u32 s16, s16, 0x4000
	s_addc_u32 s17, s17, 0
	s_mov_b32 m0, s28
	ds_read_b128 v[190:193], v168 offset:32768
	ds_read_b128 v[194:197], v168 offset:33792
	ds_read_b128 v[198:201], v168 offset:34816
	ds_read_b128 v[202:205], v168 offset:35840
	ds_read_b128 v[206:209], v168 offset:36864
	ds_read_b128 v[210:213], v168 offset:37888
	ds_read_b128 v[214:217], v168 offset:38912
	ds_read_b128 v[218:221], v168 offset:39936
	global_load_lds_dwordx4 v144, s[16:17]
	s_mov_b32 m0, s29
	s_nop 0
	global_load_lds_dwordx4 v140, s[16:17]
	s_waitcnt vmcnt(8)
	s_waitcnt lgkmcnt(0)
	s_barrier
	s_setprio 1
	s_waitcnt lgkmcnt(0)
	v_mfma_f32_16x16x32_bf16 v[126:129], v[130:133], v[190:193], v[126:129]
	v_mfma_f32_16x16x32_bf16 v[122:125], v[158:161], v[190:193], v[122:125]
	v_mfma_f32_16x16x32_bf16 v[118:121], v[130:133], v[198:201], v[118:121]
	v_mfma_f32_16x16x32_bf16 v[114:117], v[158:161], v[198:201], v[114:117]
	v_mfma_f32_16x16x32_bf16 v[110:113], v[130:133], v[206:209], v[110:113]
	v_mfma_f32_16x16x32_bf16 v[106:109], v[158:161], v[206:209], v[106:109]
	v_mfma_f32_16x16x32_bf16 v[102:105], v[130:133], v[214:217], v[102:105]
	v_mfma_f32_16x16x32_bf16 v[98:101], v[158:161], v[214:217], v[98:101]
	v_mfma_f32_16x16x32_bf16 v[126:129], v[134:137], v[194:197], v[126:129]
	v_mfma_f32_16x16x32_bf16 v[122:125], v[170:173], v[194:197], v[122:125]
	v_mfma_f32_16x16x32_bf16 v[118:121], v[134:137], v[202:205], v[118:121]
	v_mfma_f32_16x16x32_bf16 v[114:117], v[170:173], v[202:205], v[114:117]
	v_mfma_f32_16x16x32_bf16 v[110:113], v[134:137], v[210:213], v[110:113]
	v_mfma_f32_16x16x32_bf16 v[106:109], v[170:173], v[210:213], v[106:109]
	v_mfma_f32_16x16x32_bf16 v[102:105], v[134:137], v[218:221], v[102:105]
	v_mfma_f32_16x16x32_bf16 v[98:101], v[170:173], v[218:221], v[98:101]
	v_mfma_f32_16x16x32_bf16 v[62:65], v[174:177], v[190:193], v[62:65]
	v_mfma_f32_16x16x32_bf16 v[58:61], v[182:185], v[190:193], v[58:61]
	v_mfma_f32_16x16x32_bf16 v[54:57], v[174:177], v[198:201], v[54:57]
	v_mfma_f32_16x16x32_bf16 v[50:53], v[182:185], v[198:201], v[50:53]
	v_mfma_f32_16x16x32_bf16 v[46:49], v[174:177], v[206:209], v[46:49]
	v_mfma_f32_16x16x32_bf16 v[42:45], v[182:185], v[206:209], v[42:45]
	v_mfma_f32_16x16x32_bf16 v[38:41], v[174:177], v[214:217], v[38:41]
	v_mfma_f32_16x16x32_bf16 v[34:37], v[182:185], v[214:217], v[34:37]
	v_mfma_f32_16x16x32_bf16 v[62:65], v[178:181], v[194:197], v[62:65]
	v_mfma_f32_16x16x32_bf16 v[58:61], v[186:189], v[194:197], v[58:61]
	v_mfma_f32_16x16x32_bf16 v[54:57], v[178:181], v[202:205], v[54:57]
	v_mfma_f32_16x16x32_bf16 v[50:53], v[186:189], v[202:205], v[50:53]
	v_mfma_f32_16x16x32_bf16 v[46:49], v[178:181], v[210:213], v[46:49]
	v_mfma_f32_16x16x32_bf16 v[42:45], v[186:189], v[210:213], v[42:45]
	v_mfma_f32_16x16x32_bf16 v[38:41], v[178:181], v[218:221], v[38:41]
	v_mfma_f32_16x16x32_bf16 v[34:37], v[186:189], v[218:221], v[34:37]
	s_setprio 0
	s_barrier
	s_add_u32 s16, s14, 0x8000
	s_addc_u32 s17, s15, 0
	s_add_i32 s46, s46, s22
	s_mov_b32 m0, s46
	ds_read_b128 v[190:193], v168 offset:49152
	ds_read_b128 v[194:197], v168 offset:50176
	ds_read_b128 v[198:201], v168 offset:51200
	ds_read_b128 v[202:205], v168 offset:52224
	ds_read_b128 v[206:209], v168 offset:53248
	ds_read_b128 v[210:213], v168 offset:54272
	ds_read_b128 v[214:217], v168 offset:55296
	ds_read_b128 v[218:221], v168 offset:56320
	global_load_lds_dwordx4 v142, s[16:17]
	s_add_i32 m0, s46, 0x2000
	s_add_u32 s14, s14, 0xc000
	v_lshl_add_u64 v[162:163], s[16:17], 0, v[138:139]
	s_addc_u32 s15, s15, 0
	s_add_i32 s16, s47, s22
	global_load_lds_dwordx4 v[162:163], off
	s_mov_b32 m0, s16
	s_nop 0
	global_load_lds_dwordx4 v142, s[14:15]
	s_add_i32 m0, s16, 0x2000
	s_nop 0
	global_load_lds_dwordx4 v138, s[14:15]
	s_waitcnt vmcnt(6)
	s_waitcnt lgkmcnt(0)
	s_barrier
	s_setprio 1
	s_waitcnt lgkmcnt(0)
	v_mfma_f32_16x16x32_bf16 v[94:97], v[130:133], v[190:193], v[94:97]
	v_mfma_f32_16x16x32_bf16 v[90:93], v[158:161], v[190:193], v[90:93]
	v_mfma_f32_16x16x32_bf16 v[86:89], v[130:133], v[198:201], v[86:89]
	v_mfma_f32_16x16x32_bf16 v[82:85], v[158:161], v[198:201], v[82:85]
	v_mfma_f32_16x16x32_bf16 v[78:81], v[130:133], v[206:209], v[78:81]
	v_mfma_f32_16x16x32_bf16 v[74:77], v[158:161], v[206:209], v[74:77]
	v_mfma_f32_16x16x32_bf16 v[70:73], v[130:133], v[214:217], v[70:73]
	v_mfma_f32_16x16x32_bf16 v[66:69], v[158:161], v[214:217], v[66:69]
	v_mfma_f32_16x16x32_bf16 v[94:97], v[134:137], v[194:197], v[94:97]
	v_mfma_f32_16x16x32_bf16 v[90:93], v[170:173], v[194:197], v[90:93]
	v_mfma_f32_16x16x32_bf16 v[86:89], v[134:137], v[202:205], v[86:89]
	v_mfma_f32_16x16x32_bf16 v[82:85], v[170:173], v[202:205], v[82:85]
	v_mfma_f32_16x16x32_bf16 v[78:81], v[134:137], v[210:213], v[78:81]
	v_mfma_f32_16x16x32_bf16 v[74:77], v[170:173], v[210:213], v[74:77]
	v_mfma_f32_16x16x32_bf16 v[70:73], v[134:137], v[218:221], v[70:73]
	v_mfma_f32_16x16x32_bf16 v[66:69], v[170:173], v[218:221], v[66:69]
	v_mfma_f32_16x16x32_bf16 v[30:33], v[174:177], v[190:193], v[30:33]
	v_mfma_f32_16x16x32_bf16 v[26:29], v[182:185], v[190:193], v[26:29]
	v_mfma_f32_16x16x32_bf16 v[22:25], v[174:177], v[198:201], v[22:25]
	v_mfma_f32_16x16x32_bf16 v[18:21], v[182:185], v[198:201], v[18:21]
	v_mfma_f32_16x16x32_bf16 v[14:17], v[174:177], v[206:209], v[14:17]
	v_mfma_f32_16x16x32_bf16 v[10:13], v[182:185], v[206:209], v[10:13]
	v_mfma_f32_16x16x32_bf16 v[6:9], v[174:177], v[214:217], v[6:9]
	v_mfma_f32_16x16x32_bf16 v[2:5], v[182:185], v[214:217], v[2:5]
	v_mfma_f32_16x16x32_bf16 v[30:33], v[178:181], v[194:197], v[30:33]
	v_mfma_f32_16x16x32_bf16 v[26:29], v[186:189], v[194:197], v[26:29]
	v_mfma_f32_16x16x32_bf16 v[22:25], v[178:181], v[202:205], v[22:25]
	v_mfma_f32_16x16x32_bf16 v[18:21], v[186:189], v[202:205], v[18:21]
	v_mfma_f32_16x16x32_bf16 v[14:17], v[178:181], v[210:213], v[14:17]
	v_mfma_f32_16x16x32_bf16 v[10:13], v[186:189], v[210:213], v[10:13]
	v_mfma_f32_16x16x32_bf16 v[6:9], v[178:181], v[218:221], v[6:9]
	v_mfma_f32_16x16x32_bf16 v[2:5], v[186:189], v[218:221], v[2:5]
	s_setprio 0
	s_barrier
	s_add_i32 s45, s45, 2
	s_add_u32 s10, s10, 0x10000
	s_addc_u32 s11, s11, 0
	s_add_u32 s43, s43, 0x10000
	s_addc_u32 s44, s44, 0
	s_cmp_gt_u32 s45, 5
	s_cbranch_scc0 .LBB0_2685
	s_and_b64 vcc, exec, s[6:7]
	s_cbranch_vccz .LBB0_2688
	s_barrier

; #define PG8_STAGE(bufoff, gbase, voff) do { _Pragma("unroll") for (int _i = 0; _i < 2; ++_i) \
;         __builtin_amdgcn_global_load_lds((const unsigned*)((const char*)(gbase) + (voff)[_i]), (LAS unsigned*)(lds + (bufoff) + ldsw + _i * 8192), 16, 0, 0); } while (0)
; #define PG8_LDA(dst, b, h) do { _Pragma("unroll") for (int m = 0; m < 4; ++m) _Pragma("unroll") for (int k = 0; k < 2; ++k) dst[m][k] = *(const LAS bf16x8*)(lds + PG8_SA(b, h) + aoff + m * 2048 + k * 1024); } while (0)
; #define PG8_LDB(dst, b, h) do { _Pragma("unroll") for (int n = 0; n < 2; ++n) _Pragma("unroll") for (int k = 0; k < 2; ++k) dst[n][k] = *(const LAS bf16x8*)(lds + PG8_SB(b, h) + boff + n * 2048 + k * 1024); } while (0)
; #define PG8_WAIT_V(n) asm volatile("s_waitcnt vmcnt(" #n ")" ::: "memory")
; #define PG8_WAIT_L(n) asm volatile("s_waitcnt lgkmcnt(" #n ")" ::: "memory")
; #define PG8_BAR __builtin_amdgcn_s_barrier()
; #define PG8_SCHED __builtin_amdgcn_sched_barrier(0)
; template <class Epi, class Sched, bool I8 = false>
; __device__ __forceinline__ void gemm_phase(LAS unsigned char* lds, const Gemm g, const Sched& S, const Epi& E) {
;     ...
;             PG8_LDB(B0, 0, 0); PG8_LDB(B1, 0, 1); PG8_SCHED; PG8_LDA(At, 0, 0); PG8_STAGE(PG8_SA(1, 1), a1 + hstepA, voffA);
;             PG8_WAIT_V(8); PG8_WAIT_L(0); PG8_BAR; PG8_MMA(0, 0, At, B0); PG8_MMA(0, 1, At, B1); PG8_BAR; PG8_SCHED;
;             PG8_LDA(At, 0, 1); PG8_STAGE(PG8_SB(0, 0), b2, voffB); PG8_STAGE(PG8_SB(0, 1), b2 + hstepB, voffB); PG8_STAGE(PG8_SA(0, 0), a2, voffA);
;             PG8_WAIT_V(8); PG8_WAIT_L(0); PG8_BAR; PG8_MMA(1, 0, At, B0); PG8_MMA(1, 1, At, B1); PG8_BAR; PG8_SCHED;
.LBB0_3744:
	ds_read_b128 v[130:133], v231
	ds_read_b128 v[134:137], v231 offset:1024
	ds_read_b128 v[138:141], v231 offset:2048
	ds_read_b128 v[142:145], v231 offset:3072
	ds_read_b128 v[146:149], v232
	ds_read_b128 v[150:153], v232 offset:1024
	ds_read_b128 v[154:157], v232 offset:2048
	ds_read_b128 v[158:161], v232 offset:3072
	s_add_u32 s34, s30, 0x4000
	s_addc_u32 s35, s31, 0
	s_cmp_eq_u32 s59, 60
	s_cselect_b32 s38, s23, s34
	s_cselect_b32 s39, s5, s35
	s_cselect_b32 s36, s29, s57
	s_cselect_b32 s37, s21, s58
	s_add_u32 s34, s38, 0x8000
	s_addc_u32 s35, s39, 0
	s_sub_u32 s98, s30, 0x4000
	s_subb_u32 s99, s31, 0
	s_mov_b32 m0, s51
	s_nop 0
	global_load_lds_dwordx4 v194, s[98:99]
	s_mov_b32 m0, s52
	s_nop 0
	global_load_lds_dwordx4 v198, s[98:99]
	s_add_i32 m0, s44, 0xc000
	ds_read_b128 v[162:165], v233
	ds_read_b128 v[166:169], v233 offset:1024
	ds_read_b128 v[170:173], v233 offset:2048
	ds_read_b128 v[174:177], v233 offset:3072
	ds_read_b128 v[178:181], v233 offset:4096
	ds_read_b128 v[182:185], v233 offset:5120
	ds_read_b128 v[186:189], v233 offset:6144
	ds_read_b128 v[190:193], v233 offset:7168
	global_load_lds_dwordx4 v204, s[30:31]
	s_add_i32 m0, s44, 0xe000
	s_nop 0
	global_load_lds_dwordx4 v206, s[30:31]
	s_waitcnt vmcnt(8)
	s_waitcnt lgkmcnt(0)
	s_barrier
	s_setprio 1
	s_waitcnt lgkmcnt(0)
	v_mfma_f32_16x16x32_bf16 v[126:129], v[130:133], v[162:165], v[126:129]
	v_mfma_f32_16x16x32_bf16 v[122:125], v[138:141], v[162:165], v[122:125]
	v_mfma_f32_16x16x32_bf16 v[118:121], v[130:133], v[170:173], v[118:121]
	v_mfma_f32_16x16x32_bf16 v[110:113], v[138:141], v[170:173], v[110:113]
	v_mfma_f32_16x16x32_bf16 v[102:105], v[130:133], v[178:181], v[102:105]
	v_mfma_f32_16x16x32_bf16 v[94:97], v[138:141], v[178:181], v[94:97]
	v_mfma_f32_16x16x32_bf16 v[86:89], v[130:133], v[186:189], v[86:89]
	v_mfma_f32_16x16x32_bf16 v[78:81], v[138:141], v[186:189], v[78:81]
	v_mfma_f32_16x16x32_bf16 v[126:129], v[134:137], v[166:169], v[126:129]
	v_mfma_f32_16x16x32_bf16 v[122:125], v[142:145], v[166:169], v[122:125]
	v_mfma_f32_16x16x32_bf16 v[118:121], v[134:137], v[174:177], v[118:121]
	v_mfma_f32_16x16x32_bf16 v[110:113], v[142:145], v[174:177], v[110:113]
	v_mfma_f32_16x16x32_bf16 v[102:105], v[134:137], v[182:185], v[102:105]
	v_mfma_f32_16x16x32_bf16 v[94:97], v[142:145], v[182:185], v[94:97]
	v_mfma_f32_16x16x32_bf16 v[86:89], v[134:137], v[190:193], v[86:89]
	v_mfma_f32_16x16x32_bf16 v[78:81], v[142:145], v[190:193], v[78:81]
	v_mfma_f32_16x16x32_bf16 v[114:117], v[146:149], v[162:165], v[114:117]
	v_mfma_f32_16x16x32_bf16 v[106:109], v[154:157], v[162:165], v[106:109]
	v_mfma_f32_16x16x32_bf16 v[98:101], v[146:149], v[170:173], v[98:101]
	v_mfma_f32_16x16x32_bf16 v[90:93], v[154:157], v[170:173], v[90:93]
	v_mfma_f32_16x16x32_bf16 v[82:85], v[146:149], v[178:181], v[82:85]
	v_mfma_f32_16x16x32_bf16 v[74:77], v[154:157], v[178:181], v[74:77]
	v_mfma_f32_16x16x32_bf16 v[70:73], v[146:149], v[186:189], v[70:73]
	v_mfma_f32_16x16x32_bf16 v[66:69], v[154:157], v[186:189], v[66:69]
	v_mfma_f32_16x16x32_bf16 v[114:117], v[150:153], v[166:169], v[114:117]
	v_mfma_f32_16x16x32_bf16 v[106:109], v[158:161], v[166:169], v[106:109]
	v_mfma_f32_16x16x32_bf16 v[98:101], v[150:153], v[174:177], v[98:101]
	v_mfma_f32_16x16x32_bf16 v[90:93], v[158:161], v[174:177], v[90:93]
	v_mfma_f32_16x16x32_bf16 v[82:85], v[150:153], v[182:185], v[82:85]
	v_mfma_f32_16x16x32_bf16 v[74:77], v[158:161], v[182:185], v[74:77]
	v_mfma_f32_16x16x32_bf16 v[70:73], v[150:153], v[190:193], v[70:73]
	v_mfma_f32_16x16x32_bf16 v[66:69], v[158:161], v[190:193], v[66:69]
	s_setprio 0
	s_barrier
	s_add_i32 s60, s55, s43
	s_mov_b32 m0, s60
	ds_read_b128 v[162:165], v233 offset:16384
	ds_read_b128 v[166:169], v233 offset:17408
	ds_read_b128 v[170:173], v233 offset:18432
	ds_read_b128 v[174:177], v233 offset:19456
	ds_read_b128 v[178:181], v233 offset:20480
	ds_read_b128 v[182:185], v233 offset:21504
	ds_read_b128 v[186:189], v233 offset:22528
	ds_read_b128 v[190:193], v233 offset:23552
	global_load_lds_dwordx4 v196, s[36:37]
	s_add_i32 m0, s60, 0x2000
	s_add_u32 s60, s36, 0x4000
	s_addc_u32 s61, s37, 0
	s_add_i32 s62, s56, s43
	global_load_lds_dwordx4 v200, s[36:37]
	s_mov_b32 m0, s62
	s_nop 0
	global_load_lds_dwordx4 v196, s[60:61]
	s_add_i32 m0, s62, 0x2000
	s_nop 0
	global_load_lds_dwordx4 v200, s[60:61]
	s_waitcnt vmcnt(6)
	s_waitcnt lgkmcnt(0)
	s_barrier
	s_setprio 1
	s_waitcnt lgkmcnt(0)
	v_mfma_f32_16x16x32_bf16 v[62:65], v[130:133], v[162:165], v[62:65]
	v_mfma_f32_16x16x32_bf16 v[58:61], v[138:141], v[162:165], v[58:61]
	v_mfma_f32_16x16x32_bf16 v[54:57], v[130:133], v[170:173], v[54:57]
	v_mfma_f32_16x16x32_bf16 v[46:49], v[138:141], v[170:173], v[46:49]
	v_mfma_f32_16x16x32_bf16 v[38:41], v[130:133], v[178:181], v[38:41]
	v_mfma_f32_16x16x32_bf16 v[30:33], v[138:141], v[178:181], v[30:33]
	v_mfma_f32_16x16x32_bf16 v[22:25], v[130:133], v[186:189], v[22:25]
	v_mfma_f32_16x16x32_bf16 v[14:17], v[138:141], v[186:189], v[14:17]
	v_mfma_f32_16x16x32_bf16 v[62:65], v[134:137], v[166:169], v[62:65]
	v_mfma_f32_16x16x32_bf16 v[58:61], v[142:145], v[166:169], v[58:61]
	v_mfma_f32_16x16x32_bf16 v[54:57], v[134:137], v[174:177], v[54:57]
	v_mfma_f32_16x16x32_bf16 v[46:49], v[142:145], v[174:177], v[46:49]
	v_mfma_f32_16x16x32_bf16 v[38:41], v[134:137], v[182:185], v[38:41]
	v_mfma_f32_16x16x32_bf16 v[30:33], v[142:145], v[182:185], v[30:33]
	v_mfma_f32_16x16x32_bf16 v[22:25], v[134:137], v[190:193], v[22:25]
	v_mfma_f32_16x16x32_bf16 v[14:17], v[142:145], v[190:193], v[14:17]
	v_mfma_f32_16x16x32_bf16 v[50:53], v[146:149], v[162:165], v[50:53]
	v_mfma_f32_16x16x32_bf16 v[42:45], v[154:157], v[162:165], v[42:45]
	v_mfma_f32_16x16x32_bf16 v[34:37], v[146:149], v[170:173], v[34:37]
	v_mfma_f32_16x16x32_bf16 v[26:29], v[154:157], v[170:173], v[26:29]
	v_mfma_f32_16x16x32_bf16 v[18:21], v[146:149], v[178:181], v[18:21]
	v_mfma_f32_16x16x32_bf16 v[10:13], v[154:157], v[178:181], v[10:13]
	v_mfma_f32_16x16x32_bf16 v[6:9], v[146:149], v[186:189], v[6:9]
	v_mfma_f32_16x16x32_bf16 v[2:5], v[154:157], v[186:189], v[2:5]
	v_mfma_f32_16x16x32_bf16 v[50:53], v[150:153], v[166:169], v[50:53]
	v_mfma_f32_16x16x32_bf16 v[42:45], v[158:161], v[166:169], v[42:45]
	v_mfma_f32_16x16x32_bf16 v[34:37], v[150:153], v[174:177], v[34:37]
	v_mfma_f32_16x16x32_bf16 v[26:29], v[158:161], v[174:177], v[26:29]
	v_mfma_f32_16x16x32_bf16 v[18:21], v[150:153], v[182:185], v[18:21]
	v_mfma_f32_16x16x32_bf16 v[10:13], v[158:161], v[182:185], v[10:13]
	v_mfma_f32_16x16x32_bf16 v[6:9], v[150:153], v[190:193], v[6:9]
	v_mfma_f32_16x16x32_bf16 v[2:5], v[158:161], v[190:193], v[2:5]
	s_setprio 0
	s_barrier
; #define PG8_STAGE(bufoff, gbase, voff) do { _Pragma("unroll") for (int _i = 0; _i < 2; ++_i) \
;         __builtin_amdgcn_global_load_lds((const unsigned*)((const char*)(gbase) + (voff)[_i]), (LAS unsigned*)(lds + (bufoff) + ldsw + _i * 8192), 16, 0, 0); } while (0)
; #define PG8_LDA(dst, b, h) do { _Pragma("unroll") for (int m = 0; m < 4; ++m) _Pragma("unroll") for (int k = 0; k < 2; ++k) dst[m][k] = *(const LAS bf16x8*)(lds + PG8_SA(b, h) + aoff + m * 2048 + k * 1024); } while (0)
; #define PG8_LDB(dst, b, h) do { _Pragma("unroll") for (int n = 0; n < 2; ++n) _Pragma("unroll") for (int k = 0; k < 2; ++k) dst[n][k] = *(const LAS bf16x8*)(lds + PG8_SB(b, h) + boff + n * 2048 + k * 1024); } while (0)
; #define PG8_WAIT_V(n) asm volatile("s_waitcnt vmcnt(" #n ")" ::: "memory")
; #define PG8_WAIT_L(n) asm volatile("s_waitcnt lgkmcnt(" #n ")" ::: "memory")
; #define PG8_BAR __builtin_amdgcn_s_barrier()
; #define PG8_SCHED __builtin_amdgcn_sched_barrier(0)
; template <class Epi, class Sched, bool I8 = false>
; __device__ __forceinline__ void gemm_phase(LAS unsigned char* lds, const Gemm g, const Sched& S, const Epi& E) {
;     ...
;         for (int t = 0; t < nt; t += 2) {
;             const bool last = (t == nt - 2);
;     ...
;             PG8_LDB(B0, 1, 0); PG8_LDB(B1, 1, 1); PG8_SCHED; PG8_LDA(At, 1, 0); PG8_STAGE(PG8_SA(0, 1), a2 + hstepA, voffA);
;             PG8_WAIT_V(8); PG8_WAIT_L(0); PG8_BAR; PG8_MMA(0, 0, At, B0); PG8_MMA(0, 1, At, B1); PG8_BAR; PG8_SCHED;
;             PG8_LDA(At, 1, 1); PG8_STAGE(PG8_SB(1, 0), b3, voffB); PG8_STAGE(PG8_SB(1, 1), b3 + hstepB, voffB); PG8_STAGE(PG8_SA(1, 0), a3, voffA);
;             PG8_WAIT_V(8); PG8_WAIT_L(0); PG8_BAR; PG8_MMA(1, 0, At, B0); PG8_MMA(1, 1, At, B1); PG8_BAR; PG8_SCHED;
	s_add_i32 s60, 0, 0x18000
	s_add_i32 s61, 0, 0x1c000
	v_add_u32_e32 v142, s60, v230
	v_add_u32_e32 v158, s61, v230
	ds_read_b128 v[130:133], v142
	ds_read_b128 v[134:137], v142 offset:1024
	ds_read_b128 v[138:141], v142 offset:2048
	ds_read_b128 v[142:145], v142 offset:3072
	ds_read_b128 v[146:149], v158
	ds_read_b128 v[150:153], v158 offset:1024
	ds_read_b128 v[154:157], v158 offset:2048
	ds_read_b128 v[158:161], v158 offset:3072
	s_mov_b32 m0, s44
	s_nop 0
	global_load_lds_dwordx4 v194, s[38:39]
	s_mov_b32 m0, s45
	s_nop 0
	global_load_lds_dwordx4 v198, s[38:39]
	s_add_u32 s38, s38, 0x4000
	s_addc_u32 s39, s39, 0
	s_mov_b32 m0, s46
	ds_read_b128 v[162:165], v233 offset:32768
	ds_read_b128 v[166:169], v233 offset:33792
	ds_read_b128 v[170:173], v233 offset:34816
	ds_read_b128 v[174:177], v233 offset:35840
	ds_read_b128 v[178:181], v233 offset:36864
	ds_read_b128 v[182:185], v233 offset:37888
	ds_read_b128 v[186:189], v233 offset:38912
	ds_read_b128 v[190:193], v233 offset:39936
	global_load_lds_dwordx4 v194, s[38:39]
	s_mov_b32 m0, s47
	s_nop 0
	global_load_lds_dwordx4 v198, s[38:39]
	s_waitcnt vmcnt(8)
	s_waitcnt lgkmcnt(0)
	s_barrier
	s_setprio 1
	s_waitcnt lgkmcnt(0)
	v_mfma_f32_16x16x32_bf16 v[126:129], v[130:133], v[162:165], v[126:129]
	v_mfma_f32_16x16x32_bf16 v[122:125], v[138:141], v[162:165], v[122:125]
	v_mfma_f32_16x16x32_bf16 v[118:121], v[130:133], v[170:173], v[118:121]
	v_mfma_f32_16x16x32_bf16 v[110:113], v[138:141], v[170:173], v[110:113]
	v_mfma_f32_16x16x32_bf16 v[102:105], v[130:133], v[178:181], v[102:105]
	v_mfma_f32_16x16x32_bf16 v[94:97], v[138:141], v[178:181], v[94:97]
	v_mfma_f32_16x16x32_bf16 v[86:89], v[130:133], v[186:189], v[86:89]
	v_mfma_f32_16x16x32_bf16 v[78:81], v[138:141], v[186:189], v[78:81]
	v_mfma_f32_16x16x32_bf16 v[126:129], v[134:137], v[166:169], v[126:129]
	v_mfma_f32_16x16x32_bf16 v[122:125], v[142:145], v[166:169], v[122:125]
	v_mfma_f32_16x16x32_bf16 v[118:121], v[134:137], v[174:177], v[118:121]
	v_mfma_f32_16x16x32_bf16 v[110:113], v[142:145], v[174:177], v[110:113]
	v_mfma_f32_16x16x32_bf16 v[102:105], v[134:137], v[182:185], v[102:105]
	v_mfma_f32_16x16x32_bf16 v[94:97], v[142:145], v[182:185], v[94:97]
	v_mfma_f32_16x16x32_bf16 v[86:89], v[134:137], v[190:193], v[86:89]
	v_mfma_f32_16x16x32_bf16 v[78:81], v[142:145], v[190:193], v[78:81]
	v_mfma_f32_16x16x32_bf16 v[114:117], v[146:149], v[162:165], v[114:117]
	v_mfma_f32_16x16x32_bf16 v[106:109], v[154:157], v[162:165], v[106:109]
	v_mfma_f32_16x16x32_bf16 v[98:101], v[146:149], v[170:173], v[98:101]
	v_mfma_f32_16x16x32_bf16 v[90:93], v[154:157], v[170:173], v[90:93]
	v_mfma_f32_16x16x32_bf16 v[82:85], v[146:149], v[178:181], v[82:85]
	v_mfma_f32_16x16x32_bf16 v[74:77], v[154:157], v[178:181], v[74:77]
	v_mfma_f32_16x16x32_bf16 v[70:73], v[146:149], v[186:189], v[70:73]
	v_mfma_f32_16x16x32_bf16 v[66:69], v[154:157], v[186:189], v[66:69]
	v_mfma_f32_16x16x32_bf16 v[114:117], v[150:153], v[166:169], v[114:117]
	v_mfma_f32_16x16x32_bf16 v[106:109], v[158:161], v[166:169], v[106:109]
	v_mfma_f32_16x16x32_bf16 v[98:101], v[150:153], v[174:177], v[98:101]
	v_mfma_f32_16x16x32_bf16 v[90:93], v[158:161], v[174:177], v[90:93]
	v_mfma_f32_16x16x32_bf16 v[82:85], v[150:153], v[182:185], v[82:85]
	v_mfma_f32_16x16x32_bf16 v[74:77], v[158:161], v[182:185], v[74:77]
	v_mfma_f32_16x16x32_bf16 v[70:73], v[150:153], v[190:193], v[70:73]
	v_mfma_f32_16x16x32_bf16 v[66:69], v[158:161], v[190:193], v[66:69]
	s_setprio 0
	s_barrier
	s_add_u32 s38, s36, 0x8000
	s_addc_u32 s39, s37, 0
	s_add_i32 s60, s60, s43
	s_mov_b32 m0, s60
	ds_read_b128 v[162:165], v233 offset:49152
	ds_read_b128 v[166:169], v233 offset:50176
	ds_read_b128 v[170:173], v233 offset:51200
	ds_read_b128 v[174:177], v233 offset:52224
	ds_read_b128 v[178:181], v233 offset:53248
	ds_read_b128 v[182:185], v233 offset:54272
	ds_read_b128 v[186:189], v233 offset:55296
	ds_read_b128 v[190:193], v233 offset:56320
	global_load_lds_dwordx4 v196, s[38:39]
	s_add_i32 m0, s60, 0x2000
	s_add_u32 s36, s36, 0xc000
	v_lshl_add_u64 v[212:213], s[38:39], 0, v[200:201]
	s_addc_u32 s37, s37, 0
	s_add_i32 s38, s61, s43
	global_load_lds_dwordx4 v[212:213], off
	s_mov_b32 m0, s38
	s_nop 0
	global_load_lds_dwordx4 v196, s[36:37]
	s_add_i32 m0, s38, 0x2000
	s_nop 0
	global_load_lds_dwordx4 v200, s[36:37]
	s_waitcnt vmcnt(6)
	s_waitcnt lgkmcnt(0)
	s_barrier
	s_setprio 1
	s_waitcnt lgkmcnt(0)
	v_mfma_f32_16x16x32_bf16 v[62:65], v[130:133], v[162:165], v[62:65]
	v_mfma_f32_16x16x32_bf16 v[58:61], v[138:141], v[162:165], v[58:61]
	v_mfma_f32_16x16x32_bf16 v[54:57], v[130:133], v[170:173], v[54:57]
	v_mfma_f32_16x16x32_bf16 v[46:49], v[138:141], v[170:173], v[46:49]
	v_mfma_f32_16x16x32_bf16 v[38:41], v[130:133], v[178:181], v[38:41]
	v_mfma_f32_16x16x32_bf16 v[30:33], v[138:141], v[178:181], v[30:33]
	v_mfma_f32_16x16x32_bf16 v[22:25], v[130:133], v[186:189], v[22:25]
	v_mfma_f32_16x16x32_bf16 v[14:17], v[138:141], v[186:189], v[14:17]
	v_mfma_f32_16x16x32_bf16 v[62:65], v[134:137], v[166:169], v[62:65]
	v_mfma_f32_16x16x32_bf16 v[58:61], v[142:145], v[166:169], v[58:61]
	v_mfma_f32_16x16x32_bf16 v[54:57], v[134:137], v[174:177], v[54:57]
	v_mfma_f32_16x16x32_bf16 v[46:49], v[142:145], v[174:177], v[46:49]
	v_mfma_f32_16x16x32_bf16 v[38:41], v[134:137], v[182:185], v[38:41]
	v_mfma_f32_16x16x32_bf16 v[30:33], v[142:145], v[182:185], v[30:33]
	v_mfma_f32_16x16x32_bf16 v[22:25], v[134:137], v[190:193], v[22:25]
	v_mfma_f32_16x16x32_bf16 v[14:17], v[142:145], v[190:193], v[14:17]
	v_mfma_f32_16x16x32_bf16 v[50:53], v[146:149], v[162:165], v[50:53]
	v_mfma_f32_16x16x32_bf16 v[42:45], v[154:157], v[162:165], v[42:45]
	v_mfma_f32_16x16x32_bf16 v[34:37], v[146:149], v[170:173], v[34:37]
	v_mfma_f32_16x16x32_bf16 v[26:29], v[154:157], v[170:173], v[26:29]
	v_mfma_f32_16x16x32_bf16 v[18:21], v[146:149], v[178:181], v[18:21]
	v_mfma_f32_16x16x32_bf16 v[10:13], v[154:157], v[178:181], v[10:13]
	v_mfma_f32_16x16x32_bf16 v[6:9], v[146:149], v[186:189], v[6:9]
	v_mfma_f32_16x16x32_bf16 v[2:5], v[154:157], v[186:189], v[2:5]
	v_mfma_f32_16x16x32_bf16 v[50:53], v[150:153], v[166:169], v[50:53]
	v_mfma_f32_16x16x32_bf16 v[42:45], v[158:161], v[166:169], v[42:45]
	v_mfma_f32_16x16x32_bf16 v[34:37], v[150:153], v[174:177], v[34:37]
	v_mfma_f32_16x16x32_bf16 v[26:29], v[158:161], v[174:177], v[26:29]
	v_mfma_f32_16x16x32_bf16 v[18:21], v[150:153], v[182:185], v[18:21]
	v_mfma_f32_16x16x32_bf16 v[10:13], v[158:161], v[182:185], v[10:13]
	v_mfma_f32_16x16x32_bf16 v[6:9], v[150:153], v[190:193], v[6:9]
	v_mfma_f32_16x16x32_bf16 v[2:5], v[158:161], v[190:193], v[2:5]
	s_setprio 0
	s_barrier
	s_add_i32 s59, s59, 2
	s_add_u32 s30, s30, 0x10000
	s_addc_u32 s31, s31, 0
	s_add_u32 s57, s57, 0x10000
	s_addc_u32 s58, s58, 0
	s_cmp_gt_u32 s59, 61
	s_cbranch_scc0 .LBB0_3744
	s_and_b64 vcc, exec, s[6:7]
	s_cbranch_vccz .LBB0_3747
	s_barrier

; #define PG8_STAGE(bufoff, gbase, voff) do { _Pragma("unroll") for (int _i = 0; _i < 2; ++_i) \
;         __builtin_amdgcn_global_load_lds((const unsigned*)((const char*)(gbase) + (voff)[_i]), (LAS unsigned*)(lds + (bufoff) + ldsw + _i * 8192), 16, 0, 0); } while (0)
; #define PG8_LDA(dst, b, h) do { _Pragma("unroll") for (int m = 0; m < 4; ++m) _Pragma("unroll") for (int k = 0; k < 2; ++k) dst[m][k] = *(const LAS bf16x8*)(lds + PG8_SA(b, h) + aoff + m * 2048 + k * 1024); } while (0)
; #define PG8_LDB(dst, b, h) do { _Pragma("unroll") for (int n = 0; n < 2; ++n) _Pragma("unroll") for (int k = 0; k < 2; ++k) dst[n][k] = *(const LAS bf16x8*)(lds + PG8_SB(b, h) + boff + n * 2048 + k * 1024); } while (0)
; #define PG8_WAIT_V(n) asm volatile("s_waitcnt vmcnt(" #n ")" ::: "memory")
; #define PG8_WAIT_L(n) asm volatile("s_waitcnt lgkmcnt(" #n ")" ::: "memory")
; #define PG8_BAR __builtin_amdgcn_s_barrier()
; #define PG8_SCHED __builtin_amdgcn_sched_barrier(0)
; template <class Epi, class Sched, bool I8 = false>
; __device__ __forceinline__ void gemm_phase(LAS unsigned char* lds, const Gemm g, const Sched& S, const Epi& E) {
;     ...
;             PG8_LDB(B0, 0, 0); PG8_LDB(B1, 0, 1); PG8_SCHED; PG8_LDA(At, 0, 0); PG8_STAGE(PG8_SA(1, 1), a1 + hstepA, voffA);
;             PG8_WAIT_V(8); PG8_WAIT_L(0); PG8_BAR; PG8_MMA(0, 0, At, B0); PG8_MMA(0, 1, At, B1); PG8_BAR; PG8_SCHED;
;             PG8_LDA(At, 0, 1); PG8_STAGE(PG8_SB(0, 0), b2, voffB); PG8_STAGE(PG8_SB(0, 1), b2 + hstepB, voffB); PG8_STAGE(PG8_SA(0, 0), a2, voffA);
;             PG8_WAIT_V(8); PG8_WAIT_L(0); PG8_BAR; PG8_MMA(1, 0, At, B0); PG8_MMA(1, 1, At, B1); PG8_BAR; PG8_SCHED;
.LBB0_4168:
	ds_read_b128 v[66:69], v178
	ds_read_b128 v[70:73], v178 offset:1024
	ds_read_b128 v[74:77], v178 offset:2048
	ds_read_b128 v[78:81], v178 offset:3072
	ds_read_b128 v[146:149], v179
	ds_read_b128 v[150:153], v179 offset:1024
	ds_read_b128 v[172:175], v179 offset:2048
	ds_read_b128 v[182:185], v179 offset:3072
	s_add_u32 s22, s20, 0x4000
	s_addc_u32 s23, s21, 0
	s_cmpk_eq_i32 s51, 0x52
	s_cselect_b32 s26, s0, s22
	s_cselect_b32 s27, s1, s23
	s_cselect_b32 s24, s18, s49
	s_cselect_b32 s25, s19, s50
	s_add_u32 s22, s26, 0x8000
	s_addc_u32 s23, s27, 0
	s_sub_u32 s98, s20, 0x4000
	s_subb_u32 s99, s21, 0
	s_mov_b32 m0, s39
	s_nop 0
	global_load_lds_dwordx4 v154, s[98:99]
	s_mov_b32 m0, s40
	s_nop 0
	global_load_lds_dwordx4 v158, s[98:99]
	s_add_i32 m0, s34, 0xc000
	ds_read_b128 v[186:189], v180
	ds_read_b128 v[190:193], v180 offset:1024
	ds_read_b128 v[194:197], v180 offset:2048
	ds_read_b128 v[198:201], v180 offset:3072
	ds_read_b128 v[202:205], v180 offset:4096
	ds_read_b128 v[206:209], v180 offset:5120
	ds_read_b128 v[210:213], v180 offset:6144
	ds_read_b128 v[214:217], v180 offset:7168
	global_load_lds_dwordx4 v164, s[20:21]
	s_add_i32 m0, s34, 0xe000
	s_nop 0
	global_load_lds_dwordx4 v166, s[20:21]
	s_waitcnt vmcnt(8)
	s_waitcnt lgkmcnt(0)
	s_barrier
	s_setprio 1
	s_waitcnt lgkmcnt(0)
	v_mfma_i32_16x16x64_i8 v[142:145], v[66:69], v[186:189], v[142:145]
	v_mfma_i32_16x16x64_i8 v[138:141], v[74:77], v[186:189], v[138:141]
	v_mfma_i32_16x16x64_i8 v[126:129], v[66:69], v[194:197], v[126:129]
	v_mfma_i32_16x16x64_i8 v[122:125], v[74:77], v[194:197], v[122:125]
	v_mfma_i32_16x16x64_i8 v[110:113], v[66:69], v[202:205], v[110:113]
	v_mfma_i32_16x16x64_i8 v[106:109], v[74:77], v[202:205], v[106:109]
	v_mfma_i32_16x16x64_i8 v[94:97], v[66:69], v[210:213], v[94:97]
	v_mfma_i32_16x16x64_i8 v[90:93], v[74:77], v[210:213], v[90:93]
	v_mfma_i32_16x16x64_i8 v[142:145], v[70:73], v[190:193], v[142:145]
	v_mfma_i32_16x16x64_i8 v[138:141], v[78:81], v[190:193], v[138:141]
	v_mfma_i32_16x16x64_i8 v[126:129], v[70:73], v[198:201], v[126:129]
	v_mfma_i32_16x16x64_i8 v[122:125], v[78:81], v[198:201], v[122:125]
	v_mfma_i32_16x16x64_i8 v[110:113], v[70:73], v[206:209], v[110:113]
	v_mfma_i32_16x16x64_i8 v[106:109], v[78:81], v[206:209], v[106:109]
	v_mfma_i32_16x16x64_i8 v[94:97], v[70:73], v[214:217], v[94:97]
	v_mfma_i32_16x16x64_i8 v[90:93], v[78:81], v[214:217], v[90:93]
	v_mfma_i32_16x16x64_i8 v[134:137], v[146:149], v[186:189], v[134:137]
	v_mfma_i32_16x16x64_i8 v[130:133], v[172:175], v[186:189], v[130:133]
	v_mfma_i32_16x16x64_i8 v[118:121], v[146:149], v[194:197], v[118:121]
	v_mfma_i32_16x16x64_i8 v[114:117], v[172:175], v[194:197], v[114:117]
	v_mfma_i32_16x16x64_i8 v[102:105], v[146:149], v[202:205], v[102:105]
	v_mfma_i32_16x16x64_i8 v[98:101], v[172:175], v[202:205], v[98:101]
	v_mfma_i32_16x16x64_i8 v[86:89], v[146:149], v[210:213], v[86:89]
	v_mfma_i32_16x16x64_i8 v[82:85], v[172:175], v[210:213], v[82:85]
	v_mfma_i32_16x16x64_i8 v[134:137], v[150:153], v[190:193], v[134:137]
	v_mfma_i32_16x16x64_i8 v[130:133], v[182:185], v[190:193], v[130:133]
	v_mfma_i32_16x16x64_i8 v[118:121], v[150:153], v[198:201], v[118:121]
	v_mfma_i32_16x16x64_i8 v[114:117], v[182:185], v[198:201], v[114:117]
	v_mfma_i32_16x16x64_i8 v[102:105], v[150:153], v[206:209], v[102:105]
	v_mfma_i32_16x16x64_i8 v[98:101], v[182:185], v[206:209], v[98:101]
	v_mfma_i32_16x16x64_i8 v[86:89], v[150:153], v[214:217], v[86:89]
	v_mfma_i32_16x16x64_i8 v[82:85], v[182:185], v[214:217], v[82:85]
	s_setprio 0
	s_barrier
	s_add_i32 s52, s43, s33
	s_mov_b32 m0, s52
	ds_read_b128 v[186:189], v180 offset:16384
	ds_read_b128 v[190:193], v180 offset:17408
	ds_read_b128 v[194:197], v180 offset:18432
	ds_read_b128 v[198:201], v180 offset:19456
	ds_read_b128 v[202:205], v180 offset:20480
	ds_read_b128 v[206:209], v180 offset:21504
	ds_read_b128 v[210:213], v180 offset:22528
	ds_read_b128 v[214:217], v180 offset:23552
	global_load_lds_dwordx4 v156, s[24:25]
	s_add_i32 m0, s52, 0x2000
	s_add_u32 s52, s24, 0x4000
	s_addc_u32 s53, s25, 0
	s_add_i32 s54, s44, s33
	global_load_lds_dwordx4 v160, s[24:25]
	s_mov_b32 m0, s54
	s_nop 0
	global_load_lds_dwordx4 v156, s[52:53]
	s_add_i32 m0, s54, 0x2000
	s_nop 0
	global_load_lds_dwordx4 v160, s[52:53]
	s_waitcnt vmcnt(6)
	s_waitcnt lgkmcnt(0)
	s_barrier
	s_setprio 1
	s_waitcnt lgkmcnt(0)
	v_mfma_i32_16x16x64_i8 v[62:65], v[66:69], v[186:189], v[62:65]
	v_mfma_i32_16x16x64_i8 v[58:61], v[74:77], v[186:189], v[58:61]
	v_mfma_i32_16x16x64_i8 v[46:49], v[66:69], v[194:197], v[46:49]
	v_mfma_i32_16x16x64_i8 v[42:45], v[74:77], v[194:197], v[42:45]
	v_mfma_i32_16x16x64_i8 v[30:33], v[66:69], v[202:205], v[30:33]
	v_mfma_i32_16x16x64_i8 v[26:29], v[74:77], v[202:205], v[26:29]
	v_mfma_i32_16x16x64_i8 v[14:17], v[66:69], v[210:213], v[14:17]
	v_mfma_i32_16x16x64_i8 v[10:13], v[74:77], v[210:213], v[10:13]
	v_mfma_i32_16x16x64_i8 v[62:65], v[70:73], v[190:193], v[62:65]
	v_mfma_i32_16x16x64_i8 v[58:61], v[78:81], v[190:193], v[58:61]
	v_mfma_i32_16x16x64_i8 v[46:49], v[70:73], v[198:201], v[46:49]
	v_mfma_i32_16x16x64_i8 v[42:45], v[78:81], v[198:201], v[42:45]
	v_mfma_i32_16x16x64_i8 v[30:33], v[70:73], v[206:209], v[30:33]
	v_mfma_i32_16x16x64_i8 v[26:29], v[78:81], v[206:209], v[26:29]
	v_mfma_i32_16x16x64_i8 v[14:17], v[70:73], v[214:217], v[14:17]
	v_mfma_i32_16x16x64_i8 v[10:13], v[78:81], v[214:217], v[10:13]
	v_mfma_i32_16x16x64_i8 v[54:57], v[146:149], v[186:189], v[54:57]
	v_mfma_i32_16x16x64_i8 v[50:53], v[172:175], v[186:189], v[50:53]
	v_mfma_i32_16x16x64_i8 v[38:41], v[146:149], v[194:197], v[38:41]
	v_mfma_i32_16x16x64_i8 v[34:37], v[172:175], v[194:197], v[34:37]
	v_mfma_i32_16x16x64_i8 v[22:25], v[146:149], v[202:205], v[22:25]
	v_mfma_i32_16x16x64_i8 v[18:21], v[172:175], v[202:205], v[18:21]
	v_mfma_i32_16x16x64_i8 v[6:9], v[146:149], v[210:213], v[6:9]
	v_mfma_i32_16x16x64_i8 v[2:5], v[172:175], v[210:213], v[2:5]
	v_mfma_i32_16x16x64_i8 v[54:57], v[150:153], v[190:193], v[54:57]
	v_mfma_i32_16x16x64_i8 v[50:53], v[182:185], v[190:193], v[50:53]
	v_mfma_i32_16x16x64_i8 v[38:41], v[150:153], v[198:201], v[38:41]
	v_mfma_i32_16x16x64_i8 v[34:37], v[182:185], v[198:201], v[34:37]
	v_mfma_i32_16x16x64_i8 v[22:25], v[150:153], v[206:209], v[22:25]
	v_mfma_i32_16x16x64_i8 v[18:21], v[182:185], v[206:209], v[18:21]
	v_mfma_i32_16x16x64_i8 v[6:9], v[150:153], v[214:217], v[6:9]
	v_mfma_i32_16x16x64_i8 v[2:5], v[182:185], v[214:217], v[2:5]
	s_setprio 0
	s_barrier
; #define PG8_STAGE(bufoff, gbase, voff) do { _Pragma("unroll") for (int _i = 0; _i < 2; ++_i) \
;         __builtin_amdgcn_global_load_lds((const unsigned*)((const char*)(gbase) + (voff)[_i]), (LAS unsigned*)(lds + (bufoff) + ldsw + _i * 8192), 16, 0, 0); } while (0)
; #define PG8_LDA(dst, b, h) do { _Pragma("unroll") for (int m = 0; m < 4; ++m) _Pragma("unroll") for (int k = 0; k < 2; ++k) dst[m][k] = *(const LAS bf16x8*)(lds + PG8_SA(b, h) + aoff + m * 2048 + k * 1024); } while (0)
; #define PG8_LDB(dst, b, h) do { _Pragma("unroll") for (int n = 0; n < 2; ++n) _Pragma("unroll") for (int k = 0; k < 2; ++k) dst[n][k] = *(const LAS bf16x8*)(lds + PG8_SB(b, h) + boff + n * 2048 + k * 1024); } while (0)
; #define PG8_WAIT_V(n) asm volatile("s_waitcnt vmcnt(" #n ")" ::: "memory")
; #define PG8_WAIT_L(n) asm volatile("s_waitcnt lgkmcnt(" #n ")" ::: "memory")
; #define PG8_BAR __builtin_amdgcn_s_barrier()
; #define PG8_SCHED __builtin_amdgcn_sched_barrier(0)
; template <class Epi, class Sched, bool I8 = false>
; __device__ __forceinline__ void gemm_phase(LAS unsigned char* lds, const Gemm g, const Sched& S, const Epi& E) {
;     ...
;         for (int t = 0; t < nt; t += 2) {
;             const bool last = (t == nt - 2);
;     ...
;             PG8_LDB(B0, 1, 0); PG8_LDB(B1, 1, 1); PG8_SCHED; PG8_LDA(At, 1, 0); PG8_STAGE(PG8_SA(0, 1), a2 + hstepA, voffA);
;             PG8_WAIT_V(8); PG8_WAIT_L(0); PG8_BAR; PG8_MMA(0, 0, At, B0); PG8_MMA(0, 1, At, B1); PG8_BAR; PG8_SCHED;
;             PG8_LDA(At, 1, 1); PG8_STAGE(PG8_SB(1, 0), b3, voffB); PG8_STAGE(PG8_SB(1, 1), b3 + hstepB, voffB); PG8_STAGE(PG8_SA(1, 0), a3, voffA);
;             PG8_WAIT_V(8); PG8_WAIT_L(0); PG8_BAR; PG8_MMA(1, 0, At, B0); PG8_MMA(1, 1, At, B1); PG8_BAR; PG8_SCHED;
	s_add_i32 s52, 0, 0x18000
	s_add_i32 s53, 0, 0x1c000
	v_add_u32_e32 v78, s52, v176
	v_add_u32_e32 v162, s53, v176
	ds_read_b128 v[66:69], v78
	ds_read_b128 v[70:73], v78 offset:1024
	ds_read_b128 v[74:77], v78 offset:2048
	ds_read_b128 v[78:81], v78 offset:3072
	ds_read_b128 v[146:149], v162
	ds_read_b128 v[150:153], v162 offset:1024
	ds_read_b128 v[172:175], v162 offset:2048
	ds_read_b128 v[182:185], v162 offset:3072
	s_mov_b32 m0, s34
	s_nop 0
	global_load_lds_dwordx4 v154, s[26:27]
	s_mov_b32 m0, s35
	s_nop 0
	global_load_lds_dwordx4 v158, s[26:27]
	s_add_u32 s26, s26, 0x4000
	s_addc_u32 s27, s27, 0
	s_mov_b32 m0, s36
	ds_read_b128 v[186:189], v180 offset:32768
	ds_read_b128 v[190:193], v180 offset:33792
	ds_read_b128 v[194:197], v180 offset:34816
	ds_read_b128 v[198:201], v180 offset:35840
	ds_read_b128 v[202:205], v180 offset:36864
	ds_read_b128 v[206:209], v180 offset:37888
	ds_read_b128 v[210:213], v180 offset:38912
	ds_read_b128 v[214:217], v180 offset:39936
	global_load_lds_dwordx4 v154, s[26:27]
	s_mov_b32 m0, s37
	s_nop 0
	global_load_lds_dwordx4 v158, s[26:27]
	s_waitcnt vmcnt(8)
	s_waitcnt lgkmcnt(0)
	s_barrier
	s_setprio 1
	s_waitcnt lgkmcnt(0)
	v_mfma_i32_16x16x64_i8 v[142:145], v[66:69], v[186:189], v[142:145]
	v_mfma_i32_16x16x64_i8 v[138:141], v[74:77], v[186:189], v[138:141]
	v_mfma_i32_16x16x64_i8 v[126:129], v[66:69], v[194:197], v[126:129]
	v_mfma_i32_16x16x64_i8 v[122:125], v[74:77], v[194:197], v[122:125]
	v_mfma_i32_16x16x64_i8 v[110:113], v[66:69], v[202:205], v[110:113]
	v_mfma_i32_16x16x64_i8 v[106:109], v[74:77], v[202:205], v[106:109]
	v_mfma_i32_16x16x64_i8 v[94:97], v[66:69], v[210:213], v[94:97]
	v_mfma_i32_16x16x64_i8 v[90:93], v[74:77], v[210:213], v[90:93]
	v_mfma_i32_16x16x64_i8 v[142:145], v[70:73], v[190:193], v[142:145]
	v_mfma_i32_16x16x64_i8 v[138:141], v[78:81], v[190:193], v[138:141]
	v_mfma_i32_16x16x64_i8 v[126:129], v[70:73], v[198:201], v[126:129]
	v_mfma_i32_16x16x64_i8 v[122:125], v[78:81], v[198:201], v[122:125]
	v_mfma_i32_16x16x64_i8 v[110:113], v[70:73], v[206:209], v[110:113]
	v_mfma_i32_16x16x64_i8 v[106:109], v[78:81], v[206:209], v[106:109]
	v_mfma_i32_16x16x64_i8 v[94:97], v[70:73], v[214:217], v[94:97]
	v_mfma_i32_16x16x64_i8 v[90:93], v[78:81], v[214:217], v[90:93]
	v_mfma_i32_16x16x64_i8 v[134:137], v[146:149], v[186:189], v[134:137]
	v_mfma_i32_16x16x64_i8 v[130:133], v[172:175], v[186:189], v[130:133]
	v_mfma_i32_16x16x64_i8 v[118:121], v[146:149], v[194:197], v[118:121]
	v_mfma_i32_16x16x64_i8 v[114:117], v[172:175], v[194:197], v[114:117]
	v_mfma_i32_16x16x64_i8 v[102:105], v[146:149], v[202:205], v[102:105]
	v_mfma_i32_16x16x64_i8 v[98:101], v[172:175], v[202:205], v[98:101]
	v_mfma_i32_16x16x64_i8 v[86:89], v[146:149], v[210:213], v[86:89]
	v_mfma_i32_16x16x64_i8 v[82:85], v[172:175], v[210:213], v[82:85]
	v_mfma_i32_16x16x64_i8 v[134:137], v[150:153], v[190:193], v[134:137]
	v_mfma_i32_16x16x64_i8 v[130:133], v[182:185], v[190:193], v[130:133]
	v_mfma_i32_16x16x64_i8 v[118:121], v[150:153], v[198:201], v[118:121]
	v_mfma_i32_16x16x64_i8 v[114:117], v[182:185], v[198:201], v[114:117]
	v_mfma_i32_16x16x64_i8 v[102:105], v[150:153], v[206:209], v[102:105]
	v_mfma_i32_16x16x64_i8 v[98:101], v[182:185], v[206:209], v[98:101]
	v_mfma_i32_16x16x64_i8 v[86:89], v[150:153], v[214:217], v[86:89]
	v_mfma_i32_16x16x64_i8 v[82:85], v[182:185], v[214:217], v[82:85]
	s_setprio 0
	s_barrier
	s_add_u32 s26, s24, 0x8000
	s_addc_u32 s27, s25, 0
	s_add_i32 s52, s52, s33
	s_mov_b32 m0, s52
	ds_read_b128 v[186:189], v180 offset:49152
	ds_read_b128 v[190:193], v180 offset:50176
	ds_read_b128 v[194:197], v180 offset:51200
	ds_read_b128 v[198:201], v180 offset:52224
	ds_read_b128 v[202:205], v180 offset:53248
	ds_read_b128 v[206:209], v180 offset:54272
	ds_read_b128 v[210:213], v180 offset:55296
	ds_read_b128 v[214:217], v180 offset:56320
	global_load_lds_dwordx4 v156, s[26:27]
	s_add_i32 m0, s52, 0x2000
	s_add_u32 s24, s24, 0xc000
	v_lshl_add_u64 v[218:219], s[26:27], 0, v[160:161]
	s_addc_u32 s25, s25, 0
	s_add_i32 s26, s53, s33
	global_load_lds_dwordx4 v[218:219], off
	s_mov_b32 m0, s26
	s_nop 0
	global_load_lds_dwordx4 v156, s[24:25]
	s_add_i32 m0, s26, 0x2000
	s_nop 0
	global_load_lds_dwordx4 v160, s[24:25]
	s_waitcnt vmcnt(6)
	s_waitcnt lgkmcnt(0)
	s_barrier
	s_setprio 1
	s_waitcnt lgkmcnt(0)
	v_mfma_i32_16x16x64_i8 v[62:65], v[66:69], v[186:189], v[62:65]
	v_mfma_i32_16x16x64_i8 v[58:61], v[74:77], v[186:189], v[58:61]
	v_mfma_i32_16x16x64_i8 v[46:49], v[66:69], v[194:197], v[46:49]
	v_mfma_i32_16x16x64_i8 v[42:45], v[74:77], v[194:197], v[42:45]
	v_mfma_i32_16x16x64_i8 v[30:33], v[66:69], v[202:205], v[30:33]
	v_mfma_i32_16x16x64_i8 v[26:29], v[74:77], v[202:205], v[26:29]
	v_mfma_i32_16x16x64_i8 v[14:17], v[66:69], v[210:213], v[14:17]
	v_mfma_i32_16x16x64_i8 v[10:13], v[74:77], v[210:213], v[10:13]
	v_mfma_i32_16x16x64_i8 v[62:65], v[70:73], v[190:193], v[62:65]
	v_mfma_i32_16x16x64_i8 v[58:61], v[78:81], v[190:193], v[58:61]
	v_mfma_i32_16x16x64_i8 v[46:49], v[70:73], v[198:201], v[46:49]
	v_mfma_i32_16x16x64_i8 v[42:45], v[78:81], v[198:201], v[42:45]
	v_mfma_i32_16x16x64_i8 v[30:33], v[70:73], v[206:209], v[30:33]
	v_mfma_i32_16x16x64_i8 v[26:29], v[78:81], v[206:209], v[26:29]
	v_mfma_i32_16x16x64_i8 v[14:17], v[70:73], v[214:217], v[14:17]
	v_mfma_i32_16x16x64_i8 v[10:13], v[78:81], v[214:217], v[10:13]
	v_mfma_i32_16x16x64_i8 v[54:57], v[146:149], v[186:189], v[54:57]
	v_mfma_i32_16x16x64_i8 v[50:53], v[172:175], v[186:189], v[50:53]
	v_mfma_i32_16x16x64_i8 v[38:41], v[146:149], v[194:197], v[38:41]
	v_mfma_i32_16x16x64_i8 v[34:37], v[172:175], v[194:197], v[34:37]
	v_mfma_i32_16x16x64_i8 v[22:25], v[146:149], v[202:205], v[22:25]
	v_mfma_i32_16x16x64_i8 v[18:21], v[172:175], v[202:205], v[18:21]
	v_mfma_i32_16x16x64_i8 v[6:9], v[146:149], v[210:213], v[6:9]
	v_mfma_i32_16x16x64_i8 v[2:5], v[172:175], v[210:213], v[2:5]
	v_mfma_i32_16x16x64_i8 v[54:57], v[150:153], v[190:193], v[54:57]
	v_mfma_i32_16x16x64_i8 v[50:53], v[182:185], v[190:193], v[50:53]
	v_mfma_i32_16x16x64_i8 v[38:41], v[150:153], v[198:201], v[38:41]
	v_mfma_i32_16x16x64_i8 v[34:37], v[182:185], v[198:201], v[34:37]
	v_mfma_i32_16x16x64_i8 v[22:25], v[150:153], v[206:209], v[22:25]
	v_mfma_i32_16x16x64_i8 v[18:21], v[182:185], v[206:209], v[18:21]
	v_mfma_i32_16x16x64_i8 v[6:9], v[150:153], v[214:217], v[6:9]
	v_mfma_i32_16x16x64_i8 v[2:5], v[182:185], v[214:217], v[2:5]
	s_setprio 0
	s_barrier
	s_add_i32 s51, s51, 2
	s_add_u32 s20, s20, 0x10000
	s_addc_u32 s21, s21, 0
	s_add_u32 s49, s49, 0x10000
	s_addc_u32 s50, s50, 0
	s_cmpk_gt_u32 s51, 0x53
	s_cbranch_scc0 .LBB0_4168
	s_and_b64 vcc, exec, s[14:15]
	s_cbranch_vccz .LBB0_4171
	s_barrier
